# phase-range tests folded (the host always launches the cooperative kernel with the full phase range): no scalar loads around the grid barriers
# speedup vs baseline: 1.0032x; 1.0032x over previous
; __device__ __forceinline__ int lane_now() { int l; asm volatile("v_mbcnt_lo_u32_b32 %0, -1, 0\n\tv_mbcnt_hi_u32_b32 %0, -1, %0" : "=v"(l)); return l; }
; #define PG8_STAGE(bufoff, gbase, voff) do { _Pragma("unroll") for (int _i = 0; _i < 2; ++_i) \
;         __builtin_amdgcn_global_load_lds((const unsigned*)((const char*)(gbase) + (voff)[_i]), (PG8_LAS unsigned*)(lds + (bufoff) + ldsw + _i * 8192), 16, 0, 0); } while (0)
; template <class Epi, class Sched, bool ALIGN_EPI = false, bool SP2 = false>
; __device__ __forceinline__ void gemm_phase(PG8_LAS unsigned char* lds, const Gemm g, const Sched& S, const Epi& E, const int wid) {
;     const int lane = lane_now(), tid = wid * 64 + lane, wr = wid >> 2, wc = wid & 3, fr = lane & 15, fq = lane >> 4;
;     const int K = g.K, nt = K / BK;
;     unsigned voffA[2], voffB[2];
; #pragma unroll
;     for (int i = 0; i < 2; ++i) { int R, C; stage_rc(tid * 16 + i * 8192, R, C); const int Rb = Epi::PERM ? ((R & ~31) + perm32(R & 31)) : R;
;         voffA[i] = (unsigned)(R * K + C) * 2u; voffB[i] = (unsigned)(Rb * K + C) * 2u; }
;     const size_t kstep = (size_t)(BK * 2);
;     const size_t hstep = (size_t)HALF * K * 2;
;     const size_t tstep = 2 * hstep;
;     const unsigned ldsw = (unsigned)wid * 1024u;
;     const int aoff = lds_byte(wr * 64 + fr, fq * 8), boff = lds_byte(wc * 32 + fr, fq * 8);
;     ...
;     Unit cur, nxt; int ui = 0;
;     if (!S.next(0, cur)) return;
;     f32x4 acc[2][2][4][2];
; #pragma unroll
;     for (int a = 0; a < 2; ++a)
; #pragma unroll
;         for (int b = 0; b < 2; ++b)
; #pragma unroll
;             for (int m = 0; m < 4; ++m)
; #pragma unroll
;                 for (int n = 0; n < 2; ++n) acc[a][b][m][n] = (f32x4){0.f, 0.f, 0.f, 0.f};
;     bf16x8 At[4][2], B0[2][2], B1[2][2];
;     const char* cA = (const char*)g.A + (size_t)cur.pm * tstep; const char* cB = (const char*)g.Bt + (size_t)cur.pn * tstep;
;     S.a_ready(cur);
;     if constexpr (SP2) {
;         PG8_STAGE(PG8_SB(0, 0), cB, voffB); PG8_STAGE(PG8_SB(0, 1), cB + hstep, voffB); PG8_STAGE(PG8_SA(0, 0), cA, voffA); PG8_STAGE(PG8_SA(0, 1), cA + hstep, voffA);
;         if (wr == 1) PG8_BAR;
;         PG8_WAIT_V(2); PG8_BAR;
;         PG8_STAGE(PG8_SB(1, 0), cB + kstep, voffB); PG8_STAGE(PG8_SA(1, 0), cA + kstep, voffA); PG8_STAGE(PG8_SB(1, 1), cB + hstep + kstep, voffB);
;         PG8_WAIT_V(6); PG8_BAR;
.LBB0_4:
	v_readlane_b32 s0, v231, 1
	v_readlane_b32 s1, v231, 2
	s_load_dword s48, s[0:1], 0xe0
	s_movk_i32 s0, 0x2000
	s_movk_i32 s4, 0x800
	s_load_dwordx4 s[8:11], s[88:89], 0xc8
	s_ashr_i32 s1, s0, 31
	s_lshr_b32 s1, s1, 24
	s_add_i32 s0, s0, s1
	s_ashr_i32 s1, s0, 8
	s_lshl_b32 s2, s1, 6
	v_readlane_b32 s0, v231, 0
	s_cmp_ge_i32 s0, s2
	v_mbcnt_lo_u32_b32 v12, -1, 0
	v_mbcnt_hi_u32_b32 v12, -1, v12
	s_cbranch_scc1 .LBB0_40
	s_lshl_b32 s40, s92, 10
	v_lshlrev_b32_e32 v13, 4, v12
	v_add_u32_e32 v0, s40, v13
	v_add_u32_e32 v1, 0x2000, v0
	v_ashrrev_i32_e32 v2, 31, v1
	v_lshrrev_b32_e32 v2, 22, v2
	v_add_u32_e32 v2, v1, v2
	v_ashrrev_i32_e32 v2, 10, v2
	v_mul_i32_i24_e32 v3, 0x400, v2
	v_sub_u32_e32 v1, v1, v3
	v_lshrrev_b32_e32 v3, 4, v1
	v_bitop3_b32 v1, v3, v1, 32 bitop3:0x6c
	v_ashrrev_i32_e32 v3, 31, v1
	v_lshrrev_b32_e32 v3, 26, v3
	v_add_u32_e32 v3, v1, v3
	v_lshlrev_b32_e32 v5, 3, v2
	v_lshlrev_b32_e32 v2, 5, v2
	v_and_b32_e32 v14, 32, v2
	v_and_b32_e32 v2, 0xffc0, v3
	v_sub_u32_e32 v1, v1, v2
	v_ashrrev_i32_e32 v4, 6, v3
	v_and_b32_e32 v5, -16, v5
	v_lshrrev_b16_e32 v2, 7, v1
	v_add_u32_e32 v5, v4, v5
	v_and_b32_e32 v2, 1, v2
	v_and_b32_e32 v4, 3, v4
	s_mov_b32 s3, 0x7fffffe0
	v_lshrrev_b32_e32 v6, 2, v5
	v_lshlrev_b32_e32 v7, 1, v5
	v_add_u16_e32 v1, v1, v2
	v_mov_b32_e32 v2, 1
	v_and_or_b32 v4, v5, s3, v4
	v_and_b32_e32 v6, 4, v6
	v_and_b32_e32 v7, 24, v7
	v_ashrrev_i16_sdwa v1, v2, sext(v1) dst_sel:DWORD dst_unused:UNUSED_PAD src0_sel:DWORD src1_sel:BYTE_0
	v_or3_b32 v4, v4, v6, v7
	v_bfe_i32 v15, v1, 0, 16
	v_mul_lo_u32 v4, v4, s4
	v_add_u32_e32 v1, v14, v15
	v_mul_lo_u32 v16, v5, s4
	v_add_lshl_u32 v132, v4, v1, 1
	v_add_lshl_u32 v134, v1, v16, 1
	v_ashrrev_i32_e32 v1, 31, v0
	v_lshrrev_b32_e32 v1, 22, v1
	v_add_u32_e32 v1, v0, v1
	v_ashrrev_i32_e32 v1, 10, v1
	v_mul_i32_i24_e32 v3, 0x400, v1
	v_sub_u32_e32 v0, v0, v3
	v_lshrrev_b32_e32 v3, 4, v0
	v_bitop3_b32 v0, v3, v0, 32 bitop3:0x6c
	v_ashrrev_i32_e32 v3, 31, v0
	v_lshrrev_b32_e32 v3, 26, v3
	v_add_u32_e32 v3, v0, v3
	v_lshlrev_b32_e32 v5, 3, v1
	v_lshlrev_b32_e32 v1, 5, v1
	s_lshl_b32 s43, s1, 2
	v_and_b32_e32 v17, 32, v1
	v_and_b32_e32 v1, 0xc0, v3
	s_abs_i32 s44, s43
	v_sub_u32_e32 v0, v0, v1
	v_cvt_f32_u32_e32 v1, s44
	v_ashrrev_i32_e32 v4, 6, v3
	v_and_b32_e32 v5, -16, v5
	v_readlane_b32 s13, v231, 0
	v_rcp_iflag_f32_e32 v1, v1
	v_add_u32_e32 v5, v4, v5
	v_and_b32_e32 v4, 3, v4
	s_ashr_i32 s42, s13, 31
	v_and_or_b32 v4, v5, s3, v4
	s_lshr_b32 s3, s42, 29
	s_add_i32 s3, s13, s3
	v_mul_f32_e32 v1, 0x4f7ffffe, v1
	s_ashr_i32 s12, s3, 3
	s_and_b32 s3, s3, -8
	v_cvt_u32_f32_e32 v1, v1
	s_sub_i32 s3, s13, s3
	s_lshl_b32 s41, s1, 3
	s_lshr_b32 s13, s3, 31
	s_or_b32 s13, s41, s13
	s_mul_i32 s3, s13, s3
	s_sub_i32 s13, 0, s44
	v_readfirstlane_b32 s46, v1
	s_add_i32 s3, s3, s12
	s_mul_i32 s13, s13, s46
	s_ashr_i32 s12, s3, 31
	s_bfe_i32 s45, s1, 0x1001d
	s_mul_hi_u32 s13, s46, s13
	s_xor_b32 s1, s12, s45
	s_abs_i32 s12, s3
	s_add_i32 s46, s46, s13
	s_mul_hi_u32 s13, s12, s46
	s_mul_i32 s14, s13, s44
	s_ashr_i32 s5, s4, 31
	s_sub_i32 s12, s12, s14
	s_ashr_i32 s0, s92, 2
	s_lshl_b64 s[6:7], s[4:5], 8
	s_lshl_b64 s[16:17], s[4:5], 9
	s_add_i32 s14, s13, 1
	s_sub_i32 s15, s12, s44
	s_cmp_ge_u32 s12, s44
	s_cselect_b32 s13, s14, s13
	s_cselect_b32 s12, s15, s12
	s_add_i32 s14, s13, 1
	s_cmp_ge_u32 s12, s44
	s_cselect_b32 s12, s14, s13
	s_xor_b32 s12, s12, s1
	s_sub_i32 s1, s12, s1
	s_lshl_b32 s12, s1, 2
	s_sub_i32 s13, 64, s12
	s_min_i32 s13, s13, 4
	s_abs_i32 s14, s13
	v_lshrrev_b32_e32 v6, 2, v5
	v_lshlrev_b32_e32 v7, 1, v5
	v_cvt_f32_u32_e32 v1, s14
	v_and_b32_e32 v6, 4, v6
	v_and_b32_e32 v7, 24, v7
	v_ashrrev_i16_sdwa v0, v2, sext(v0) dst_sel:DWORD dst_unused:UNUSED_PAD src0_sel:DWORD src1_sel:BYTE_0
	v_or3_b32 v4, v4, v6, v7
	v_bfe_i32 v18, v0, 0, 16
	v_mul_lo_u32 v4, v4, s4
	v_add_u32_e32 v0, v17, v18
	v_mul_lo_u32 v19, v5, s4
	v_add_lshl_u32 v136, v4, v0, 1
	v_add_lshl_u32 v138, v0, v19, 1
	v_rcp_iflag_f32_e32 v0, v1
	s_sub_i32 s18, 0, s14
	s_mul_i32 s1, s1, s43
	s_sub_i32 s1, s3, s1
	v_mul_f32_e32 v0, 0x4f7ffffe, v0
	v_cvt_u32_f32_e32 v0, v0
	s_abs_i32 s15, s1
	s_xor_b32 s3, s1, s13
	s_ashr_i32 s3, s3, 31
	v_readfirstlane_b32 s19, v0
	s_mul_i32 s18, s18, s19
	s_mul_hi_u32 s18, s19, s18
	s_add_i32 s19, s19, s18
	s_mul_hi_u32 s18, s15, s19
	s_mul_i32 s19, s18, s14
	s_sub_i32 s15, s15, s19
	s_add_i32 s19, s18, 1
	s_sub_i32 s20, s15, s14
	s_cmp_ge_u32 s15, s14
	s_cselect_b32 s18, s19, s18
	s_cselect_b32 s15, s20, s15
	s_add_i32 s19, s18, 1
	s_cmp_ge_u32 s15, s14
	s_cselect_b32 s14, s19, s18
	s_xor_b32 s14, s14, s3
	s_sub_i32 s67, s14, s3
	s_mul_i32 s3, s67, s13
	s_sub_i32 s1, s1, s3
	s_add_i32 s68, s1, s12
	s_lshr_b64 s[12:13], s[4:5], 23
	s_ashr_i32 s1, s68, 31
	s_ashr_i32 s13, s67, 31
	s_mul_i32 s1, s16, s1
	s_mul_hi_u32 s3, s16, s68
	s_mul_i32 s13, s16, s13
	s_mul_hi_u32 s14, s16, s67
	s_add_i32 s1, s3, s1
	s_mul_i32 s3, s12, s68
	s_add_i32 s13, s14, s13
	s_mul_i32 s12, s12, s67
	s_add_i32 s1, s1, s3
	s_add_i32 s13, s13, s12
	s_mul_i32 s12, s16, s67
	s_waitcnt lgkmcnt(0)
	s_add_u32 s36, s10, s12
	s_addc_u32 s37, s11, s13
	s_add_i32 s47, s40, 0
	s_add_i32 m0, s47, 0x10000
	s_mul_i32 s3, s16, s68
	global_load_lds_dwordx4 v136, s[36:37]
	s_add_i32 m0, s47, 0x12000
	s_add_u32 s18, s36, s6
	global_load_lds_dwordx4 v132, s[36:37]
	s_addc_u32 s19, s37, s7
	s_add_i32 m0, s47, 0x14000
	v_mov_b32_e32 v137, 0
	global_load_lds_dwordx4 v136, s[18:19]
	s_add_i32 m0, s47, 0x16000
	s_add_u32 s38, s8, s3
	s_addc_u32 s39, s9, s1
	s_add_i32 s49, s47, 0x2000
	global_load_lds_dwordx4 v132, s[18:19]
	s_mov_b32 m0, s47
	s_add_u32 s12, s38, s6
	global_load_lds_dwordx4 v138, s[38:39]
	s_mov_b32 m0, s49
	s_addc_u32 s13, s39, s7
	s_add_i32 s50, s47, 0x4000
	global_load_lds_dwordx4 v134, s[38:39]
	s_mov_b32 m0, s50
	s_add_i32 s51, s47, 0x6000
	global_load_lds_dwordx4 v138, s[12:13]
	s_mov_b32 m0, s51
	v_mov_b32_e32 v133, v137
	global_load_lds_dwordx4 v134, s[12:13]
	s_load_dwordx4 s[12:15], s[88:89], 0x20
	v_mov_b32_e32 v139, v137
	v_mov_b32_e32 v135, v137
	s_cmp_eq_u32 s0, 1
	s_mov_b32 s52, 0
	v_lshl_add_u64 v[8:9], s[36:37], 0, v[136:137]
	v_lshl_add_u64 v[4:5], s[36:37], 0, v[132:133]
	v_lshl_add_u64 v[2:3], s[18:19], 0, v[136:137]
	v_lshl_add_u64 v[0:1], s[18:19], 0, v[132:133]
	v_lshl_add_u64 v[6:7], s[38:39], 0, v[138:139]
	s_cselect_b64 s[18:19], -1, 0
	s_cmp_lg_u32 s0, 1
	v_lshl_add_u64 v[10:11], s[38:39], 0, v[134:135]
	s_cbranch_scc1 .LBB0_9
	s_barrier

; __device__ __forceinline__ void xcd_barrier(const XcdBarrier& b, const bool leader, const unsigned G) {
;     asm volatile("s_waitcnt vmcnt(0)" ::: "memory");
;     __syncthreads();
;     if (leader) {
.LBB0_40:
	s_getreg_b32 s0, hwreg(HW_REG_XCC_ID, 0, 4)
	s_cmp_lg_u32 s92, 0
	s_mov_b64 s[4:5], 0
	s_cbranch_scc1 .LBB0_43
	v_mbcnt_lo_u32_b32 v0, -1, 0
	v_mbcnt_hi_u32_b32 v0, -1, v0
	s_nop 0
	v_cmp_eq_u32_e32 vcc, 0, v0
	s_and_b64 s[4:5], vcc, exec

; __device__ __forceinline__ unsigned xb_add(unsigned* p, unsigned v) { return __hip_atomic_fetch_add(p, v, __ATOMIC_RELAXED, __HIP_MEMORY_SCOPE_AGENT); }
; __device__ __forceinline__ unsigned xb_xcc_id() { return (unsigned)__builtin_amdgcn_s_getreg((3 << 11) | 20) & 0xFu; }
; template <bool COOP>
; __global__ void __launch_bounds__(NTHR, 2) mega(Args args) {
;     ...
;         ph_prep0(C); if (PROBE_DUP == P_PREP0) { __syncthreads(); ph_prep0(C); } if (P_PREP0 + 1 < ka->ph_hi) { if constexpr (COOP) { cg::this_grid().sync(); if (threadIdx.x == 0) (void)xb_add(&((unsigned*)(C.ws + WS_CTL))[XB_XCNT(xb_xcc_id())], 1u); } } }
.LBB0_248:
	v_lshrrev_b32_e32 v2, 20, v0
	v_lshrrev_b32_e32 v0, 10, v0
	v_or_b32_e32 v0, v0, v2
	s_movk_i32 s0, 0x3ff
	v_and_or_b32 v0, v0, s0, v1
	v_cmp_eq_u32_e32 vcc, 0, v0
	s_barrier
	s_and_saveexec_b64 s[4:5], vcc
	s_cbranch_execz .LBB0_259
	buffer_wbl2 sc1
	s_waitcnt vmcnt(0)
	s_load_dwordx2 s[6:7], s[24:25], 0x58
	v_mov_b32_e32 v2, 0
	s_mov_b64 s[8:9], exec
	v_mbcnt_lo_u32_b32 v1, s8, 0
	v_mbcnt_hi_u32_b32 v1, s9, v1
	s_waitcnt lgkmcnt(0)
	global_load_dword v0, v2, s[6:7] offset:40
	v_cmp_eq_u32_e32 vcc, 0, v1
	s_and_saveexec_b64 s[10:11], vcc
	s_cbranch_execz .LBB0_252
	s_bcnt1_i32_b64 s0, s[8:9]
	v_mov_b32_e32 v3, s0
	global_atomic_add v3, v2, v3, s[6:7] offset:32 sc0

; #define LAS __attribute__((address_space(3)))
; __device__ __forceinline__ int lane_now() { int l; asm volatile("v_mbcnt_lo_u32_b32 %0, -1, 0\n\tv_mbcnt_hi_u32_b32 %0, -1, %0" : "=v"(l)); return l; }
; __device__ __forceinline__ void ph_attn2(Ctx& C) {
;     const int lane = lane_now(), wave = C.wave, tid = wave * 64 + lane, r31 = lane & 31, hh = lane >> 5;
;     const bf16* z = (const bf16*)(C.ws + WS_ZQKV); bf16* og = (bf16*)(C.ws + WS_OG); float* lse_o = (float*)(C.ws + WS_LSE);
;     LAS bf16* vt = (LAS bf16*)C.lds; LAS bf16* kim = (LAS bf16*)(C.lds + 64 * AT_VTS * 2);
;     for (int unit = C.bid; unit < 1536; unit += C.nb) {
.LBB0_305:
	s_mov_b32 s100, 0
.Latt_setup:
	s_nop 0
	v_writelane_b32 v231, s88, 3
	s_load_dwordx2 s[78:79], s[88:89], 0xd0
	s_nop 0
	v_writelane_b32 v231, s89, 4
	s_nop 0
	v_readlane_b32 s0, v231, 1
	v_readlane_b32 s1, v231, 2
	s_load_dword s0, s[0:1], 0xe0
	v_readlane_b32 s1, v231, 0
	s_cmpk_gt_i32 s1, 0x5ff
	v_mbcnt_lo_u32_b32 v0, -1, 0
	v_mbcnt_hi_u32_b32 v0, -1, v0
	s_cmp_lg_u32 s100, 0
	s_cbranch_scc1 .Latt_go
	s_bitcmp1_b32 s1, 0
	s_cbranch_scc0 .Latt_go
	s_mov_b32 s100, 1
	s_branch .LBB0_326

; __device__ __forceinline__ int lane_now() { int l; asm volatile("v_mbcnt_lo_u32_b32 %0, -1, 0\n\tv_mbcnt_hi_u32_b32 %0, -1, %0" : "=v"(l)); return l; }
; __device__ __forceinline__ void ph_attn_combine(Ctx& C) {
;     const int lane = lane_now(); const bf16* og = (const bf16*)(C.ws + WS_OG); const float* lse = (const float*)(C.ws + WS_LSE); bf16* oa = (bf16*)(C.ws + WS_OATT);
;     const int ntask = S * 64;
;     for (int task = (C.bid * NWAVES + C.wave) * 64 + lane; task < ntask; task += C.nb * NTHR) { const int t = task >> 6, c8 = task & 63, h = c8 >> 3;
;         const float l0 = lse[(size_t)t * 8 + h], l1 = lse[((size_t)S + t) * 8 + h], l2 = lse[((size_t)2 * S + t) * 8 + h]; const float mx = fmaxf(l0, fmaxf(l1, l2));
.LBB0_626:
	v_readlane_b32 s0, v231, 1
	v_readlane_b32 s1, v231, 2
	s_load_dwordx2 s[4:5], s[88:89], 0xd0
	s_load_dword s48, s[0:1], 0xe0
	v_readlane_b32 s0, v231, 0
	s_lshl_b32 s0, s0, 9
	s_lshl_b32 s1, s92, 6
	s_add_i32 s1, s1, s0
	v_mbcnt_lo_u32_b32 v0, -1, 0
	v_mbcnt_hi_u32_b32 v0, -1, v0
	s_mov_b32 s0, 0x100000
	v_add_u32_e32 v6, s1, v0
	v_cmp_gt_i32_e32 vcc, s0, v6
	s_and_saveexec_b64 s[2:3], vcc
	s_cbranch_execz .LBB0_631
	v_and_b32_e32 v4, 63, v0
	v_lshrrev_b32_e32 v0, 1, v0
	v_and_b32_e32 v2, 28, v0
	v_mov_b32_e32 v3, 0
	s_waitcnt lgkmcnt(0)
	v_lshl_add_u64 v[0:1], s[4:5], 0, v[2:3]
	s_mov_b64 s[6:7], 0x1ea00000
	v_lshlrev_b32_e32 v2, 4, v4
	v_lshl_add_u64 v[0:1], v[0:1], 0, s[6:7]
	v_lshl_add_u64 v[2:3], s[4:5], 0, v[2:3]
	s_mov_b64 s[6:7], 0x1ba00000
	s_lshl_b32 s0, s48, 9
	v_lshl_add_u64 v[4:5], v[2:3], 0, s[6:7]
	s_mov_b64 s[6:7], 0
	s_mov_b64 s[8:9], 0x4000
	s_mov_b64 s[10:11], 0x8000
	s_mov_b32 s1, 0xfffff

; __device__ __forceinline__ void xcd_barrier(const XcdBarrier& b, const bool leader, const unsigned G) {
;     asm volatile("s_waitcnt vmcnt(0)" ::: "memory");
;     __syncthreads();
;     if (leader) {
.LBB0_643:
	s_getreg_b32 s0, hwreg(HW_REG_XCC_ID, 0, 4)
	s_cmp_lg_u32 s92, 0
	s_mov_b64 s[6:7], 0
	s_cbranch_scc1 .LBB0_646
	v_mbcnt_lo_u32_b32 v0, -1, 0
	v_mbcnt_hi_u32_b32 v0, -1, v0
	s_nop 0
	v_cmp_eq_u32_e32 vcc, 0, v0
	s_and_b64 s[6:7], vcc, exec

; #define LAS __attribute__((address_space(3)))
; __device__ __forceinline__ int lane_now() { int l; asm volatile("v_mbcnt_lo_u32_b32 %0, -1, 0\n\tv_mbcnt_hi_u32_b32 %0, -1, %0" : "=v"(l)); return l; }
; template <int role> __device__ __forceinline__ void ph_scan1m_r(Ctx& C) {
;     const int lane0 = lane_now(), wave = C.wave, itl = wave & 3;
;     const bf16* g_r = (const bf16*)(C.ws + WS_R); const bf16* g_v = (const bf16*)(C.ws + WS_V); const bf16* g_nkk = (const bf16*)(C.ws + WS_NKK); const bf16* g_k = (const bf16*)(C.ws + WS_KRAW);
;     const bf16* g_lw = (const bf16*)(C.ws + WS_LW); const bf16* g_a = (const bf16*)(C.ws + WS_A); const float* k_a = C.ka->in[14];
;     bf16* g_out = role ? (bf16*)(C.ws + WS_YL) : (bf16*)(C.dout + DO_QT); float* g_pu = (float*)(C.ws + WS_PU);
;     LAS unsigned char* L = C.lds + wave * SM_WAVE;
;     LAS bf16* imKR = (LAS bf16*)(L + SM_KR); LAS bf16* imBK = (LAS bf16*)(L + SM_BK); LAS bf16* imBGT = (LAS bf16*)(L + SM_BGT); LAS float* gT = (LAS float*)(L + SM_GT); LAS bf16* imVT = (LAS bf16*)(L + SM_VT);
;     LAS float* MT = (LAS float*)(L + SM_BK);
;     const int nitems = NCHAIN * NCK;
;     for (int base = C.bid * 4; base < nitems; base += C.nb * 4) {
;         const int item = base + itl; if (item >= nitems) continue;
;         const int chain = item / NCK, chunk = item % NCK, z = chain >> 4, h = chain & 15; const size_t zoff = (size_t)z * S * RW; const f32x2 ka2 = *(const f32x2*)(k_a + h * 64 + 2 * (lane0 & 31)), k1 = (f32x2){1.0f - ka2.x, 1.0f - ka2.y};
; __device__ __forceinline__ void ph_scan1m(Ctx& C) {
;     if (C.wave >> 2) { __builtin_amdgcn_s_setprio(2); ph_scan1m_r<1>(C); __builtin_amdgcn_s_setprio(0); } else ph_scan1m_r<0>(C); }
.LBB0_699:
	s_load_dwordx2 s[20:21], s[88:89], 0xd0
	v_readlane_b32 s0, v231, 1
	v_readlane_b32 s1, v231, 2
	s_load_dword s48, s[0:1], 0xe0
	s_mul_i32 s0, s92, 0x4500
	s_waitcnt lgkmcnt(0)
	s_add_u32 s40, s20, 0x17a00000
	s_addc_u32 s41, s21, 0
	s_add_i32 s42, s0, 0
	s_cmp_lt_u32 s92, 4
	s_mov_b64 s[2:3], -1
	s_cbranch_scc1 .LBB0_712
	s_setprio 2
	v_readlane_b32 s0, v231, 0
	s_cmpk_gt_i32 s0, 0xff
	v_mbcnt_lo_u32_b32 v140, -1, 0
	v_mbcnt_hi_u32_b32 v140, -1, v140
	s_cbranch_scc1 .LBB0_711
	s_and_b32 s25, s92, 3
	s_add_u32 s43, s20, 0x13a00000
	s_addc_u32 s44, s21, 0
	s_add_u32 s45, s20, 0x15a00000
	s_addc_u32 s46, s21, 0
	s_add_u32 s47, s20, 0x19a00000
	s_addc_u32 s49, s21, 0
	s_add_u32 s50, s20, 0x3a00000
	s_addc_u32 s51, s21, 0
	s_add_u32 s52, s20, 0x7a00000
	s_load_dwordx2 s[0:1], s[88:89], 0x70
	s_addc_u32 s53, s21, 0
	s_add_u32 s54, s20, 0x1ba00000
	v_readlane_b32 s2, v231, 0
	s_addc_u32 s55, s21, 0
	s_lshl_b32 s56, s2, 2
	v_lshlrev_b32_e32 v0, 3, v140
	s_waitcnt vmcnt(0)
	v_and_b32_e32 v112, 0xf8, v0
	v_mov_b32_e32 v113, 0
	s_add_u32 s57, s20, 0xda04000
	s_waitcnt lgkmcnt(0)
	v_lshl_add_u64 v[114:115], s[0:1], 0, v[112:113]
	s_addc_u32 s58, s21, 0
	s_lshl_b32 s59, s48, 2
	s_mov_b32 s23, 0
	s_movk_i32 s60, 0x400
	s_mov_b32 s24, 0x3fb8aa3b
	s_movk_i32 s61, 0x90
	s_movk_i32 s62, 0x480
	s_movk_i32 s63, 0xa0
	s_movk_i32 s64, 0x50
	s_mov_b32 s65, 0x5040100
	s_mov_b32 s66, 0x7060302
	s_movk_i32 s67, 0x60
	s_movk_i32 s68, 0x240
	s_movk_i32 s69, 0x2000
	v_mov_b32_e32 v141, 0x3fb8aa3b
	s_branch .LBB0_706

; __device__ __forceinline__ int lane_now() { int l; asm volatile("v_mbcnt_lo_u32_b32 %0, -1, 0\n\tv_mbcnt_hi_u32_b32 %0, -1, %0" : "=v"(l)); return l; }
; __device__ __forceinline__ void ph_scan2b(Ctx& C) {
;     const int lane = lane_now(), wave = C.wave, tid = wave * 64 + lane; const float* g_pu = (const float*)(C.ws + WS_PU); float* g_s0 = (float*)(C.ws + WS_S0);
;     constexpr int SLOT = 18432, NSLOT = 6, AHEAD = 5;
;     for (int task = C.bid; task < NCHAIN * 8; task += C.nb) { const int chain = task >> 3, rg = task & 7, row = rg * 8 + wave;
;         const float* Pb = g_pu + (size_t)chain * NCK * 8192;
.LBB0_778:
	v_readlane_b32 s0, v231, 1
	v_readlane_b32 s1, v231, 2
	s_load_dwordx2 s[4:5], s[88:89], 0xd0
	s_load_dword s48, s[0:1], 0xe0
	v_readlane_b32 s0, v231, 0
	s_cmpk_gt_i32 s0, 0xff
	v_mbcnt_lo_u32_b32 v4, -1, 0
	v_mbcnt_hi_u32_b32 v4, -1, v4
	s_cbranch_scc1 .LBB0_834
	s_waitcnt lgkmcnt(0)
	s_add_u32 s40, s4, 0xda00000
	s_addc_u32 s46, s5, 0
	s_lshl_b32 s34, s92, 6
	s_lshl_b32 s0, s92, 10
	s_cmp_lt_i32 s92, 2
	s_cselect_b64 s[6:7], -1, 0
	s_cmp_gt_i32 s92, 1
	s_cselect_b64 s[8:9], -1, 0
	s_add_i32 s35, s0, 0
	s_add_i32 s0, s35, 0x8800
	v_writelane_b32 v231, s0, 3
	s_add_i32 s0, s35, 0x11800
	v_writelane_b32 v231, s0, 5
	s_add_i32 s0, s35, 0x4000
	v_writelane_b32 v231, s0, 6
	s_add_i32 s0, s35, 0xd000
	v_add_lshl_u32 v0, v4, s34, 2
	v_writelane_b32 v231, s0, 7
	v_ashrrev_i32_e32 v1, 31, v0
	v_ashrrev_i32_e32 v5, 31, v4
	s_waitcnt vmcnt(0)
	v_lshl_add_u32 v146, v4, 2, 0
	v_readlane_b32 s49, v231, 0
	s_mov_b32 s11, 0
	s_add_i32 s36, s35, 0x6800
	s_add_i32 s38, s35, 0xd800
	s_add_i32 s39, s35, 0xf800
	v_lshl_add_u32 v147, s92, 8, v146
	v_lshlrev_b64 v[2:3], 2, v[0:1]
	v_lshlrev_b64 v[4:5], 2, v[4:5]
	s_add_i32 s41, s35, 0x2000
	s_mov_b64 s[12:13], 0x8000
	s_add_i32 s42, s35, 0x4800
	s_mov_b64 s[14:15], 0x10000
	s_add_i32 s44, s35, 0x9000
	s_add_i32 s45, s35, 0xb000
	v_cndmask_b32_e64 v148, 0, 1, s[6:7]
	s_mov_b32 s47, s49
	s_branch .LBB0_783

; __device__ __forceinline__ void ph_scan2b(Ctx& C) {
;     ...
;     asm volatile("s_waitcnt vmcnt(0)" ::: "memory"); __builtin_amdgcn_s_barrier();
.LBB0_834:
	s_waitcnt vmcnt(0)
	s_barrier
	s_getreg_b32 s0, hwreg(HW_REG_XCC_ID, 0, 4)
	s_cmp_lg_u32 s92, 0
	s_mov_b64 s[6:7], 0
	s_cbranch_scc1 .LBB0_837
	v_mbcnt_lo_u32_b32 v0, -1, 0
	v_mbcnt_hi_u32_b32 v0, -1, v0
	s_nop 0
	v_cmp_eq_u32_e32 vcc, 0, v0
	s_and_b64 s[6:7], vcc, exec

; #define LAS __attribute__((address_space(3)))
; __device__ __forceinline__ int lane_now() { int l; asm volatile("v_mbcnt_lo_u32_b32 %0, -1, 0\n\tv_mbcnt_hi_u32_b32 %0, -1, %0" : "=v"(l)); return l; }
; __device__ __forceinline__ void ph_fin4(Ctx& C) {
;     const int lane0 = lane_now(), wave = C.wave;
;     const bf16* yl = (const bf16*)(C.ws + WS_YL); const bf16* qt = (const bf16*)(C.dout + DO_QT); const float* s0 = (const float*)(C.ws + WS_S0);
;     const bf16* r = (const bf16*)(C.ws + WS_R); const bf16* kraw = (const bf16*)(C.ws + WS_KRAW); const bf16* a = (const bf16*)(C.ws + WS_A); const float* k_a = C.ka->in[14]; const float* r_k = C.ka->in[15];
;     const bf16* v = (const bf16*)(C.ws + WS_V); const bf16* gate = (const bf16*)(C.ws + WS_GATE); bf16* orw = (bf16*)(C.ws + WS_ORWKV); const float* lnw = C.ka->in[16]; const float* lnb = C.ka->in[17];
;     LAS bf16* s0img = (LAS bf16*)C.lds;
;     LAS bf16* tr = (LAS bf16*)(C.lds + 2 * 64 * F4_S0STR * 2) + C.wave * (32 * F4_TSTR);
;     for (int task = C.bid; task < 16 * NCK; task += C.nb) { const int h = task & 15, cf = task >> 4, cb = NCK - 1 - cf;
;         int lane = lane0; asm volatile("" : "+v"(lane));
;         const int r31 = lane & 31, hh = lane >> 5, tid = wave * 64 + lane;
.LBB0_890:
	v_readlane_b32 s0, v231, 1
	v_readlane_b32 s1, v231, 2
	s_load_dwordx4 s[4:7], s[88:89], 0xc8
	s_load_dword s48, s[0:1], 0xe0
	v_readlane_b32 s0, v231, 0
	s_cmpk_gt_i32 s0, 0x1ff
	s_waitcnt vmcnt(0)
	v_mbcnt_lo_u32_b32 v178, -1, 0
	v_mbcnt_hi_u32_b32 v178, -1, v178
	s_cbranch_scc1 .LBB0_897
	s_waitcnt lgkmcnt(0)
	s_add_u32 s16, s6, 0x1ba00000
	s_addc_u32 s17, s7, 0
	s_add_u32 s44, s4, 0x4000000
	s_addc_u32 s45, s5, 0
	s_add_u32 s18, s6, 0x11a00000
	s_addc_u32 s19, s7, 0
	s_add_u32 s20, s6, 0x13a00000
	s_addc_u32 s21, s7, 0
	s_add_u32 s22, s6, 0x19a00000
	s_addc_u32 s23, s7, 0
	s_add_u32 s24, s6, 0x7a00000
	s_addc_u32 s25, s7, 0
	s_add_u32 s26, s6, 0x15a00000
	s_addc_u32 s27, s7, 0
	s_load_dwordx8 s[8:15], s[88:89], 0x70
	s_add_u32 s28, s6, 0xba00000
	s_addc_u32 s29, s7, 0
	s_add_u32 s30, s6, 0x3a00000
	s_mul_i32 s0, s92, 0x1100
	s_addc_u32 s31, s7, 0
	s_add_i32 s46, s0, 0
	v_mbcnt_lo_u32_b32 v0, -1, 0
	s_lshl_b32 s47, s92, 6
	s_lshl_b32 s49, s92, 5
	s_movk_i32 s50, 0x100
	v_mov_b32_e32 v113, 0
	s_movk_i32 s51, 0x90
	s_movk_i32 s52, 0x88
	v_mov_b32_e32 v179, s46
	s_mov_b64 s[34:35], 0x4000
	s_mov_b64 s[36:37], 0x8000
	s_mov_b64 s[38:39], 0xc000
	s_mov_b64 s[40:41], 0x2000000
	s_brev_b32 s53, 64
	s_movk_i32 s54, 0x4800
	v_mov_b32_e32 v180, 0x3a27c5ac
	s_mov_b32 s55, 0xf800000
	v_mov_b32_e32 v181, 0x260
	s_movk_i32 s56, 0x7fff
	v_mbcnt_hi_u32_b32 v182, -1, v0
	v_mov_b32_e32 v183, 1
	v_readlane_b32 s57, v231, 0

; #define LAS __attribute__((address_space(3)))
; __device__ __forceinline__ void conv_natural(Ctx& C, const float* W, int K, int N, bf16* Wt, LAS float* scr) {
;     const int nkb = K / 64;
;     conv_run(C, (N / 32) * nkb, [=](int it) { const int j32 = it / nkb, kb = it % nkb; return TrItem{W + (size_t)(kb * 64) * N + j32 * 32, N, 64, Wt + (size_t)(j32 * 32) * K + kb * 64, K}; }, scr);
; }
; __device__ __forceinline__ void ph_g1b(Ctx& C) {
;     LAS float* scr = (LAS float*)(C.lds + C.wave * 16384);
;     conv_natural(C, C.ka->in[20], D, D, (bf16*)(C.ws + WS_WOUT), scr);
.LBB0_953:
	s_mov_b32 s101, 0
.Lg1b_setup:
	v_readlane_b32 s0, v231, 1
	v_readlane_b32 s1, v231, 2
	s_load_dword s52, s[0:1], 0xe0
	v_readlane_b32 s0, v231, 0
	s_load_dwordx4 s[20:23], s[88:89], 0xc8
	s_lshl_b32 s0, s0, 3
	s_add_i32 s51, s92, s0
	s_lshl_b32 s0, s92, 14
	s_waitcnt lgkmcnt(0)
	s_lshl_b32 s50, s52, 3
	s_add_i32 s53, s0, 0
	s_cmpk_gt_i32 s51, 0x7ff
	v_mbcnt_lo_u32_b32 v46, -1, 0
	v_mbcnt_hi_u32_b32 v46, -1, v46
	s_cmp_lg_u32 s101, 0
	s_cbranch_scc1 .Lg1b_go
	v_readlane_b32 s0, v231, 0
	s_nop 0
	s_bitcmp1_b32 s0, 0
	s_cbranch_scc0 .Lg1b_go
	s_mov_b32 s101, 1
	s_branch .LBB0_1086

; #define PG8_WAIT_V(n) asm volatile("s_waitcnt vmcnt(" #n ")" ::: "memory")
; #define PG8_BAR __builtin_amdgcn_s_barrier()
; template <class Epi, class Sched, bool ALIGN_EPI = false, bool SP2 = false>
; __device__ __forceinline__ void gemm_phase(PG8_LAS unsigned char* lds, const Gemm g, const Sched& S, const Epi& E, const int wid) {
;     ...
;     PG8_WAIT_V(0);
;     if constexpr (!ALIGN_EPI) { if (wr == 0) PG8_BAR; }
;     PG8_BAR;
.Lg1b_fin:
	s_waitcnt vmcnt(0) lgkmcnt(0)
	s_barrier
	s_branch .LBB0_1163
	s_getreg_b32 s0, hwreg(HW_REG_XCC_ID, 0, 4)
	s_cmp_lg_u32 s92, 0
	s_mov_b64 s[4:5], 0
	s_cbranch_scc1 .LBB0_1110
	v_mbcnt_lo_u32_b32 v0, -1, 0
	v_mbcnt_hi_u32_b32 v0, -1, v0
	s_nop 0
	v_cmp_eq_u32_e32 vcc, 0, v0
	s_and_b64 s[4:5], vcc, exec

; __device__ __forceinline__ int lane_now() { int l; asm volatile("v_mbcnt_lo_u32_b32 %0, -1, 0\n\tv_mbcnt_hi_u32_b32 %0, -1, %0" : "=v"(l)); return l; }
; template <class Epi, class Sched, bool ALIGN_EPI = false, bool SP2 = false>
; __device__ __forceinline__ void gemm_phase(PG8_LAS unsigned char* lds, const Gemm g, const Sched& S, const Epi& E, const int wid) {
;     const int lane = lane_now(), tid = wid * 64 + lane, wr = wid >> 2, wc = wid & 3, fr = lane & 15, fq = lane >> 4;
;     const int K = g.K, nt = K / BK;
;     unsigned voffA[2], voffB[2];
; #pragma unroll
;     for (int i = 0; i < 2; ++i) { int R, C; stage_rc(tid * 16 + i * 8192, R, C); const int Rb = Epi::PERM ? ((R & ~31) + perm32(R & 31)) : R;
;         voffA[i] = (unsigned)(R * K + C) * 2u; voffB[i] = (unsigned)(Rb * K + C) * 2u; }
;     const size_t kstep = (size_t)(BK * 2);
;     const size_t hstep = (size_t)HALF * K * 2;
;     const size_t tstep = 2 * hstep;
;     const unsigned ldsw = (unsigned)wid * 1024u;
;     const int aoff = lds_byte(wr * 64 + fr, fq * 8), boff = lds_byte(wc * 32 + fr, fq * 8);
;     ...
;     Unit cur, nxt; int ui = 0;
;     if (!S.next(0, cur)) return;
;     f32x4 acc[2][2][4][2];
; #pragma unroll
;     for (int a = 0; a < 2; ++a)
; #pragma unroll
;         for (int b = 0; b < 2; ++b)
; #pragma unroll
;             for (int m = 0; m < 4; ++m)
; #pragma unroll
;                 for (int n = 0; n < 2; ++n) acc[a][b][m][n] = (f32x4){0.f, 0.f, 0.f, 0.f};
;     bf16x8 At[4][2], B0[2][2], B1[2][2];
;     const char* cA = (const char*)g.A + (size_t)cur.pm * tstep; const char* cB = (const char*)g.Bt + (size_t)cur.pn * tstep;
;     S.a_ready(cur);
;     if constexpr (SP2) {
;         PG8_STAGE(PG8_SB(0, 0), cB, voffB); PG8_STAGE(PG8_SB(0, 1), cB + hstep, voffB); PG8_STAGE(PG8_SA(0, 0), cA, voffA); PG8_STAGE(PG8_SA(0, 1), cA + hstep, voffA);
;         if (wr == 1) PG8_BAR;
;         PG8_WAIT_V(2); PG8_BAR;
;         PG8_STAGE(PG8_SB(1, 0), cB + kstep, voffB); PG8_STAGE(PG8_SA(1, 0), cA + kstep, voffA); PG8_STAGE(PG8_SB(1, 1), cB + hstep + kstep, voffB);
;         PG8_WAIT_V(6); PG8_BAR;
; template <bool COOP>
; __global__ void __launch_bounds__(NTHR, 2) mega(Args args) {
;     ...
;     PH(P_GMA, { EpiMerge8<false> E{(bf16*)(C.ws + WS_MERGED), (const bf16*)(C.ws + WS_ZG)}; gemm8(C, (const bf16*)(C.ws + WS_OATT), (const bf16*)(C.ws + WS_WBA), D, 512, E); });
.LBB0_1163:
	v_readlane_b32 s0, v231, 1
	v_readlane_b32 s1, v231, 2
	s_load_dword s48, s[0:1], 0xe0
	s_movk_i32 s0, 0x800
	s_movk_i32 s4, 0x200
	s_load_dwordx2 s[6:7], s[88:89], 0xd0
	s_ashr_i32 s1, s0, 31
	s_lshr_b32 s1, s1, 24
	s_add_i32 s0, s0, s1
	s_ashr_i32 s1, s0, 8
	s_lshl_b32 s2, s1, 6
	v_readlane_b32 s0, v231, 0
	s_cmp_ge_i32 s0, s2
	v_mbcnt_lo_u32_b32 v12, -1, 0
	v_mbcnt_hi_u32_b32 v12, -1, v12
	s_cbranch_scc1 .LBB0_1186
	s_waitcnt lgkmcnt(0)
	s_add_u32 s30, s6, 0x3400000
	s_addc_u32 s31, s7, 0
	s_lshl_b32 s34, s92, 10
	v_lshl_add_u32 v0, v12, 4, s34
	v_add_u32_e32 v1, 0x2000, v0
	v_ashrrev_i32_e32 v2, 31, v1
	v_lshrrev_b32_e32 v2, 22, v2
	v_add_u32_e32 v2, v1, v2
	v_ashrrev_i32_e32 v2, 10, v2
	v_mul_i32_i24_e32 v3, 0x400, v2
	v_sub_u32_e32 v1, v1, v3
	v_lshrrev_b32_e32 v3, 4, v1
	v_bitop3_b32 v1, v3, v1, 32 bitop3:0x6c
	v_ashrrev_i32_e32 v3, 31, v1
	v_lshrrev_b32_e32 v3, 26, v3
	v_add_u32_e32 v3, v1, v3
	v_lshlrev_b32_e32 v5, 3, v2
	v_lshlrev_b32_e32 v2, 5, v2
	v_and_b32_e32 v13, 32, v2
	v_and_b32_e32 v2, 0xffc0, v3
	v_sub_u32_e32 v1, v1, v2
	v_ashrrev_i32_e32 v4, 6, v3
	v_and_b32_e32 v5, -16, v5
	v_lshrrev_b16_e32 v2, 7, v1
	v_add_u32_e32 v5, v4, v5
	v_and_b32_e32 v2, 1, v2
	v_and_b32_e32 v4, 3, v4
	s_mov_b32 s3, 0x7fffffe0
	v_lshrrev_b32_e32 v6, 2, v5
	v_lshlrev_b32_e32 v7, 1, v5
	v_add_u16_e32 v1, v1, v2
	v_mov_b32_e32 v2, 1
	v_and_or_b32 v4, v5, s3, v4
	v_and_b32_e32 v6, 4, v6
	v_and_b32_e32 v7, 24, v7
	v_ashrrev_i16_sdwa v1, v2, sext(v1) dst_sel:DWORD dst_unused:UNUSED_PAD src0_sel:DWORD src1_sel:BYTE_0
	v_or3_b32 v4, v4, v6, v7
	v_bfe_i32 v14, v1, 0, 16
	v_mul_lo_u32 v4, v4, s4
	v_add_u32_e32 v1, v13, v14
	v_mul_lo_u32 v15, v5, s4
	s_waitcnt vmcnt(0)
	v_add_lshl_u32 v128, v4, v1, 1
	v_add_lshl_u32 v130, v1, v15, 1
	v_ashrrev_i32_e32 v1, 31, v0
	v_lshrrev_b32_e32 v1, 22, v1
	v_add_u32_e32 v1, v0, v1
	v_ashrrev_i32_e32 v1, 10, v1
	v_mul_i32_i24_e32 v3, 0x400, v1
	v_sub_u32_e32 v0, v0, v3
	v_lshrrev_b32_e32 v3, 4, v0
	v_bitop3_b32 v0, v3, v0, 32 bitop3:0x6c
	v_ashrrev_i32_e32 v3, 31, v0
	v_lshrrev_b32_e32 v3, 26, v3
	v_add_u32_e32 v3, v0, v3
	v_lshlrev_b32_e32 v5, 3, v1
	v_ashrrev_i32_e32 v4, 6, v3
	v_and_b32_e32 v5, -16, v5
	v_readlane_b32 s13, v231, 0
	v_add_u32_e32 v5, v4, v5
	v_and_b32_e32 v4, 3, v4
	s_ashr_i32 s36, s13, 31
	v_and_or_b32 v4, v5, s3, v4
	s_lshr_b32 s3, s36, 29
	s_add_i32 s3, s13, s3
	s_ashr_i32 s5, s4, 31
	s_lshl_b32 s35, s1, 3
	s_ashr_i32 s12, s3, 3
	s_and_b32 s3, s3, -8
	s_ashr_i32 s0, s92, 2
	s_lshl_b64 s[8:9], s[4:5], 8
	s_lshl_b64 s[10:11], s[4:5], 9
	s_sub_i32 s3, s13, s3
	s_or_b32 s37, s35, 1
	s_cmp_lt_i32 s3, 0
	v_lshlrev_b32_e32 v1, 5, v1
	s_cselect_b32 s13, s37, s35
	s_lshl_b32 s38, s1, 2
	v_and_b32_e32 v16, 32, v1
	v_and_b32_e32 v1, 0xc0, v3
	s_abs_i32 s39, s38
	v_sub_u32_e32 v0, v0, v1
	v_cvt_f32_u32_e32 v1, s39
	s_mul_i32 s3, s13, s3
	s_sub_i32 s13, 0, s39
	s_add_i32 s3, s3, s12
	v_rcp_iflag_f32_e32 v1, v1
	s_ashr_i32 s12, s3, 31
	s_bfe_i32 s40, s1, 0x1001d
	s_xor_b32 s1, s12, s40
	v_mul_f32_e32 v1, 0x4f7ffffe, v1
	v_cvt_u32_f32_e32 v1, v1
	s_abs_i32 s12, s3
	v_lshrrev_b32_e32 v6, 2, v5
	v_lshlrev_b32_e32 v7, 1, v5
	v_readfirstlane_b32 s41, v1
	s_mul_i32 s13, s13, s41
	s_mul_hi_u32 s13, s41, s13
	s_add_i32 s41, s41, s13
	s_mul_hi_u32 s13, s12, s41
	s_mul_i32 s14, s13, s39
	s_sub_i32 s12, s12, s14
	s_add_i32 s14, s13, 1
	s_sub_i32 s15, s12, s39
	s_cmp_ge_u32 s12, s39
	s_cselect_b32 s13, s14, s13
	s_cselect_b32 s12, s15, s12
	s_add_i32 s14, s13, 1
	s_cmp_ge_u32 s12, s39
	s_cselect_b32 s12, s14, s13
	s_xor_b32 s12, s12, s1
	s_sub_i32 s1, s12, s1
	s_lshl_b32 s12, s1, 2
	s_sub_i32 s13, 64, s12
	s_min_i32 s13, s13, 4
	s_abs_i32 s14, s13
	v_cvt_f32_u32_e32 v1, s14
	v_and_b32_e32 v6, 4, v6
	v_and_b32_e32 v7, 24, v7
	v_ashrrev_i16_sdwa v0, v2, sext(v0) dst_sel:DWORD dst_unused:UNUSED_PAD src0_sel:DWORD src1_sel:BYTE_0
	v_or3_b32 v4, v4, v6, v7
	v_bfe_i32 v17, v0, 0, 16
	v_mul_lo_u32 v4, v4, s4
	v_add_u32_e32 v0, v16, v17
	v_mul_lo_u32 v18, v5, s4
	v_add_lshl_u32 v132, v4, v0, 1
	v_add_lshl_u32 v134, v0, v18, 1
	v_rcp_iflag_f32_e32 v0, v1
	s_sub_i32 s16, 0, s14
	s_mul_i32 s1, s1, s38
	s_sub_i32 s1, s3, s1
	v_mul_f32_e32 v0, 0x4f7ffffe, v0
	v_cvt_u32_f32_e32 v0, v0
	s_abs_i32 s15, s1
	s_xor_b32 s3, s1, s13
	s_ashr_i32 s3, s3, 31
	v_readfirstlane_b32 s17, v0
	s_mul_i32 s16, s16, s17
	s_mul_hi_u32 s16, s17, s16
	s_add_i32 s17, s17, s16
	s_mul_hi_u32 s16, s15, s17
	s_mul_i32 s17, s16, s14
	s_sub_i32 s15, s15, s17
	s_add_i32 s17, s16, 1
	s_sub_i32 s18, s15, s14
	s_cmp_ge_u32 s15, s14
	s_cselect_b32 s16, s17, s16
	s_cselect_b32 s15, s18, s15
	s_add_i32 s17, s16, 1
	s_cmp_ge_u32 s15, s14
	s_cselect_b32 s14, s17, s16
	s_xor_b32 s14, s14, s3
	s_sub_i32 s59, s14, s3
	s_mul_i32 s3, s59, s13
	s_sub_i32 s1, s1, s3
	s_add_i32 s60, s1, s12
	s_lshr_b64 s[12:13], s[4:5], 23
	s_ashr_i32 s1, s60, 31
	s_ashr_i32 s13, s59, 31
	s_mul_i32 s1, s10, s1
	s_mul_hi_u32 s3, s10, s60
	s_mul_i32 s13, s10, s13
	s_mul_hi_u32 s14, s10, s59
	s_add_i32 s1, s3, s1
	s_mul_i32 s3, s12, s60
	s_add_i32 s13, s14, s13
	s_mul_i32 s12, s12, s59
	s_add_i32 s1, s1, s3
	s_add_i32 s13, s13, s12
	s_mul_i32 s12, s10, s59
	s_add_u32 s28, s30, s12
	s_addc_u32 s29, s31, s13
	s_add_i32 s42, s34, 0
	s_add_i32 m0, s42, 0x10000
	s_mul_i32 s3, s10, s60
	global_load_lds_dwordx4 v132, s[28:29]
	s_add_i32 m0, s42, 0x12000
	s_add_u32 s12, s28, s8
	global_load_lds_dwordx4 v128, s[28:29]
	s_addc_u32 s13, s29, s9
	s_add_i32 m0, s42, 0x14000
	v_mov_b32_e32 v133, 0
	global_load_lds_dwordx4 v132, s[12:13]
	s_add_i32 m0, s42, 0x16000
	s_add_u32 s26, s6, s3
	s_addc_u32 s27, s7, s1
	s_add_i32 s43, s42, 0x2000
	global_load_lds_dwordx4 v128, s[12:13]
	s_mov_b32 m0, s42
	s_add_u32 s14, s26, s8
	global_load_lds_dwordx4 v134, s[26:27]
	s_mov_b32 m0, s43
	s_addc_u32 s15, s27, s9
	s_add_i32 s44, s42, 0x4000
	global_load_lds_dwordx4 v130, s[26:27]
	s_mov_b32 m0, s44
	s_add_i32 s45, s42, 0x6000
	global_load_lds_dwordx4 v134, s[14:15]
	s_mov_b32 m0, s45
	v_mov_b32_e32 v129, v133
	global_load_lds_dwordx4 v130, s[14:15]
	v_mov_b32_e32 v135, v133
	v_mov_b32_e32 v131, v133
	s_cmp_eq_u32 s0, 1
	s_mov_b32 s46, 0
	v_lshl_add_u64 v[8:9], s[28:29], 0, v[132:133]
	v_lshl_add_u64 v[4:5], s[28:29], 0, v[128:129]
	v_lshl_add_u64 v[2:3], s[12:13], 0, v[132:133]
	v_lshl_add_u64 v[0:1], s[12:13], 0, v[128:129]
	v_lshl_add_u64 v[6:7], s[26:27], 0, v[134:135]
	s_cselect_b64 s[12:13], -1, 0
	s_cmp_lg_u32 s0, 1
	v_lshl_add_u64 v[10:11], s[26:27], 0, v[130:131]
	s_cbranch_scc1 .LBB0_1168
	s_barrier

; __device__ __forceinline__ int lane_now() { int l; asm volatile("v_mbcnt_lo_u32_b32 %0, -1, 0\n\tv_mbcnt_hi_u32_b32 %0, -1, %0" : "=v"(l)); return l; }
; template <class Epi, class Sched, bool ALIGN_EPI = false, bool SP2 = false>
; __device__ __forceinline__ void gemm_phase(PG8_LAS unsigned char* lds, const Gemm g, const Sched& S, const Epi& E, const int wid) {
;     const int lane = lane_now(), tid = wid * 64 + lane, wr = wid >> 2, wc = wid & 3, fr = lane & 15, fq = lane >> 4;
;     const int K = g.K, nt = K / BK;
;     unsigned voffA[2], voffB[2];
; #pragma unroll
;     for (int i = 0; i < 2; ++i) { int R, C; stage_rc(tid * 16 + i * 8192, R, C); const int Rb = Epi::PERM ? ((R & ~31) + perm32(R & 31)) : R;
;         voffA[i] = (unsigned)(R * K + C) * 2u; voffB[i] = (unsigned)(Rb * K + C) * 2u; }
;     const size_t kstep = (size_t)(BK * 2);
;     const size_t hstep = (size_t)HALF * K * 2;
;     const size_t tstep = 2 * hstep;
;     const unsigned ldsw = (unsigned)wid * 1024u;
;     const int aoff = lds_byte(wr * 64 + fr, fq * 8), boff = lds_byte(wc * 32 + fr, fq * 8);
;     ...
;     Unit cur, nxt; int ui = 0;
;     if (!S.next(0, cur)) return;
;     f32x4 acc[2][2][4][2];
; #pragma unroll
;     for (int a = 0; a < 2; ++a)
; #pragma unroll
;         for (int b = 0; b < 2; ++b)
; #pragma unroll
;             for (int m = 0; m < 4; ++m)
; #pragma unroll
;                 for (int n = 0; n < 2; ++n) acc[a][b][m][n] = (f32x4){0.f, 0.f, 0.f, 0.f};
;     bf16x8 At[4][2], B0[2][2], B1[2][2];
;     const char* cA = (const char*)g.A + (size_t)cur.pm * tstep; const char* cB = (const char*)g.Bt + (size_t)cur.pn * tstep;
;     S.a_ready(cur);
;     if constexpr (SP2) {
;         PG8_STAGE(PG8_SB(0, 0), cB, voffB); PG8_STAGE(PG8_SB(0, 1), cB + hstep, voffB); PG8_STAGE(PG8_SA(0, 0), cA, voffA); PG8_STAGE(PG8_SA(0, 1), cA + hstep, voffA);
;         if (wr == 1) PG8_BAR;
;         PG8_WAIT_V(2); PG8_BAR;
;         PG8_STAGE(PG8_SB(1, 0), cB + kstep, voffB); PG8_STAGE(PG8_SA(1, 0), cA + kstep, voffA); PG8_STAGE(PG8_SB(1, 1), cB + hstep + kstep, voffB);
;         PG8_WAIT_V(6); PG8_BAR;
; template <bool COOP>
; __global__ void __launch_bounds__(NTHR, 2) mega(Args args) {
;     ...
;     PH(P_GMB, { EpiMerge8<true> E{(bf16*)(C.ws + WS_MERGED), (const bf16*)(C.ws + WS_ZG)}; gemm8(C, (const bf16*)(C.ws + WS_ORWKV), (const bf16*)(C.ws + WS_WBR), D, RW, E); });
.LBB0_1242:
	v_readlane_b32 s0, v231, 1
	v_readlane_b32 s1, v231, 2
	s_load_dword s48, s[0:1], 0xe0
	s_movk_i32 s0, 0x800
	s_movk_i32 s4, 0x400
	s_load_dwordx2 s[6:7], s[88:89], 0xd0
	s_ashr_i32 s1, s0, 31
	s_lshr_b32 s1, s1, 24
	s_add_i32 s0, s0, s1
	s_ashr_i32 s1, s0, 8
	s_lshl_b32 s2, s1, 6
	v_readlane_b32 s0, v231, 0
	s_cmp_ge_i32 s0, s2
	v_mbcnt_lo_u32_b32 v12, -1, 0
	v_mbcnt_hi_u32_b32 v12, -1, v12
	s_cbranch_scc1 .LBB0_1265
	s_waitcnt lgkmcnt(0)
	s_add_u32 s34, s6, 0x3a00000
	s_addc_u32 s35, s7, 0
	s_add_u32 s36, s6, 0x3600000
	s_addc_u32 s37, s7, 0
	s_lshl_b32 s38, s92, 10
	v_lshl_add_u32 v0, v12, 4, s38
	v_add_u32_e32 v1, 0x2000, v0
	v_ashrrev_i32_e32 v2, 31, v1
	v_lshrrev_b32_e32 v2, 22, v2
	v_add_u32_e32 v2, v1, v2
	v_ashrrev_i32_e32 v2, 10, v2
	v_mul_i32_i24_e32 v3, 0x400, v2
	v_sub_u32_e32 v1, v1, v3
	v_lshrrev_b32_e32 v3, 4, v1
	v_bitop3_b32 v1, v3, v1, 32 bitop3:0x6c
	v_ashrrev_i32_e32 v3, 31, v1
	v_lshrrev_b32_e32 v3, 26, v3
	v_add_u32_e32 v3, v1, v3
	v_lshlrev_b32_e32 v5, 3, v2
	v_lshlrev_b32_e32 v2, 5, v2
	v_and_b32_e32 v13, 32, v2
	v_and_b32_e32 v2, 0xffc0, v3
	v_sub_u32_e32 v1, v1, v2
	v_ashrrev_i32_e32 v4, 6, v3
	v_and_b32_e32 v5, -16, v5
	v_lshrrev_b16_e32 v2, 7, v1
	v_add_u32_e32 v5, v4, v5
	v_and_b32_e32 v2, 1, v2
	v_and_b32_e32 v4, 3, v4
	s_mov_b32 s3, 0x7fffffe0
	v_lshrrev_b32_e32 v6, 2, v5
	v_lshlrev_b32_e32 v7, 1, v5
	v_add_u16_e32 v1, v1, v2
	v_mov_b32_e32 v2, 1
	v_and_or_b32 v4, v5, s3, v4
	v_and_b32_e32 v6, 4, v6
	v_and_b32_e32 v7, 24, v7
	v_ashrrev_i16_sdwa v1, v2, sext(v1) dst_sel:DWORD dst_unused:UNUSED_PAD src0_sel:DWORD src1_sel:BYTE_0
	v_or3_b32 v4, v4, v6, v7
	v_bfe_i32 v14, v1, 0, 16
	v_mul_lo_u32 v4, v4, s4
	v_add_u32_e32 v1, v13, v14
	v_mul_lo_u32 v15, v5, s4
	s_waitcnt vmcnt(0)
	v_add_lshl_u32 v128, v4, v1, 1
	v_add_lshl_u32 v130, v1, v15, 1
	v_ashrrev_i32_e32 v1, 31, v0
	v_lshrrev_b32_e32 v1, 22, v1
	v_add_u32_e32 v1, v0, v1
	v_ashrrev_i32_e32 v1, 10, v1
	v_mul_i32_i24_e32 v3, 0x400, v1
	v_sub_u32_e32 v0, v0, v3
	v_lshrrev_b32_e32 v3, 4, v0
	v_bitop3_b32 v0, v3, v0, 32 bitop3:0x6c
	v_ashrrev_i32_e32 v3, 31, v0
	v_lshrrev_b32_e32 v3, 26, v3
	v_add_u32_e32 v3, v0, v3
	v_lshlrev_b32_e32 v5, 3, v1
	v_ashrrev_i32_e32 v4, 6, v3
	v_and_b32_e32 v5, -16, v5
	v_readlane_b32 s13, v231, 0
	v_add_u32_e32 v5, v4, v5
	v_and_b32_e32 v4, 3, v4
	s_ashr_i32 s40, s13, 31
	v_and_or_b32 v4, v5, s3, v4
	s_lshr_b32 s3, s40, 29
	s_add_i32 s3, s13, s3
	s_ashr_i32 s5, s4, 31
	s_lshl_b32 s39, s1, 3
	s_ashr_i32 s12, s3, 3
	s_and_b32 s3, s3, -8
	s_ashr_i32 s0, s92, 2
	s_lshl_b64 s[8:9], s[4:5], 8
	s_lshl_b64 s[10:11], s[4:5], 9
	s_sub_i32 s3, s13, s3
	s_or_b32 s41, s39, 1
	s_cmp_lt_i32 s3, 0
	v_lshlrev_b32_e32 v1, 5, v1
	s_cselect_b32 s13, s41, s39
	s_lshl_b32 s42, s1, 2
	v_and_b32_e32 v16, 32, v1
	v_and_b32_e32 v1, 0xc0, v3
	s_abs_i32 s43, s42
	v_sub_u32_e32 v0, v0, v1
	v_cvt_f32_u32_e32 v1, s43
	s_mul_i32 s3, s13, s3
	s_sub_i32 s13, 0, s43
	s_add_i32 s3, s3, s12
	v_rcp_iflag_f32_e32 v1, v1
	s_ashr_i32 s12, s3, 31
	s_bfe_i32 s44, s1, 0x1001d
	s_xor_b32 s1, s12, s44
	v_mul_f32_e32 v1, 0x4f7ffffe, v1
	v_cvt_u32_f32_e32 v1, v1
	s_abs_i32 s12, s3
	v_lshrrev_b32_e32 v6, 2, v5
	v_lshlrev_b32_e32 v7, 1, v5
	v_readfirstlane_b32 s45, v1
	s_mul_i32 s13, s13, s45
	s_mul_hi_u32 s13, s45, s13
	s_add_i32 s45, s45, s13
	s_mul_hi_u32 s13, s12, s45
	s_mul_i32 s14, s13, s43
	s_sub_i32 s12, s12, s14
	s_add_i32 s14, s13, 1
	s_sub_i32 s15, s12, s43
	s_cmp_ge_u32 s12, s43
	s_cselect_b32 s13, s14, s13
	s_cselect_b32 s12, s15, s12
	s_add_i32 s14, s13, 1
	s_cmp_ge_u32 s12, s43
	s_cselect_b32 s12, s14, s13
	s_xor_b32 s12, s12, s1
	s_sub_i32 s1, s12, s1
	s_lshl_b32 s12, s1, 2
	s_sub_i32 s13, 64, s12
	s_min_i32 s13, s13, 4
	s_abs_i32 s14, s13
	v_cvt_f32_u32_e32 v1, s14
	v_and_b32_e32 v6, 4, v6
	v_and_b32_e32 v7, 24, v7
	v_ashrrev_i16_sdwa v0, v2, sext(v0) dst_sel:DWORD dst_unused:UNUSED_PAD src0_sel:DWORD src1_sel:BYTE_0
	v_or3_b32 v4, v4, v6, v7
	v_bfe_i32 v17, v0, 0, 16
	v_mul_lo_u32 v4, v4, s4
	v_add_u32_e32 v0, v16, v17
	v_mul_lo_u32 v18, v5, s4
	v_add_lshl_u32 v132, v4, v0, 1
	v_add_lshl_u32 v134, v0, v18, 1
	v_rcp_iflag_f32_e32 v0, v1
	s_sub_i32 s16, 0, s14
	s_mul_i32 s1, s1, s42
	s_sub_i32 s1, s3, s1
	v_mul_f32_e32 v0, 0x4f7ffffe, v0
	v_cvt_u32_f32_e32 v0, v0
	s_abs_i32 s15, s1
	s_xor_b32 s3, s1, s13
	s_ashr_i32 s3, s3, 31
	v_readfirstlane_b32 s17, v0
	s_mul_i32 s16, s16, s17
	s_mul_hi_u32 s16, s17, s16
	s_add_i32 s17, s17, s16
	s_mul_hi_u32 s16, s15, s17
	s_mul_i32 s17, s16, s14
	s_sub_i32 s15, s15, s17
	s_add_i32 s17, s16, 1
	s_sub_i32 s18, s15, s14
	s_cmp_ge_u32 s15, s14
	s_cselect_b32 s16, s17, s16
	s_cselect_b32 s15, s18, s15
	s_add_i32 s17, s16, 1
	s_cmp_ge_u32 s15, s14
	s_cselect_b32 s14, s17, s16
	s_xor_b32 s14, s14, s3
	s_sub_i32 s64, s14, s3
	s_mul_i32 s3, s64, s13
	s_sub_i32 s1, s1, s3
	s_add_i32 s65, s1, s12
	s_lshr_b64 s[12:13], s[4:5], 23
	s_ashr_i32 s1, s65, 31
	s_ashr_i32 s13, s64, 31
	s_mul_i32 s1, s10, s1
	s_mul_hi_u32 s3, s10, s65
	s_mul_i32 s13, s10, s13
	s_mul_hi_u32 s14, s10, s64
	s_add_i32 s1, s3, s1
	s_mul_i32 s3, s12, s65
	s_add_i32 s13, s14, s13
	s_mul_i32 s12, s12, s64
	s_add_i32 s1, s1, s3
	s_add_i32 s13, s13, s12
	s_mul_i32 s12, s10, s64
	s_add_u32 s30, s36, s12
	s_addc_u32 s31, s37, s13
	s_add_i32 s46, s38, 0
	s_add_i32 m0, s46, 0x10000
	s_mul_i32 s3, s10, s65
	global_load_lds_dwordx4 v132, s[30:31]
	s_add_i32 m0, s46, 0x12000
	s_add_u32 s12, s30, s8
	global_load_lds_dwordx4 v128, s[30:31]
	s_addc_u32 s13, s31, s9
	s_add_i32 m0, s46, 0x14000
	v_mov_b32_e32 v133, 0
	global_load_lds_dwordx4 v132, s[12:13]
	s_add_i32 m0, s46, 0x16000
	s_add_u32 s28, s34, s3
	s_addc_u32 s29, s35, s1
	s_add_i32 s47, s46, 0x2000
	global_load_lds_dwordx4 v128, s[12:13]
	s_mov_b32 m0, s46
	s_add_u32 s14, s28, s8
	global_load_lds_dwordx4 v134, s[28:29]
	s_mov_b32 m0, s47
	s_addc_u32 s15, s29, s9
	s_add_i32 s49, s46, 0x4000
	global_load_lds_dwordx4 v130, s[28:29]
	s_mov_b32 m0, s49
	s_add_i32 s50, s46, 0x6000
	global_load_lds_dwordx4 v134, s[14:15]
	s_mov_b32 m0, s50
	v_mov_b32_e32 v129, v133
	global_load_lds_dwordx4 v130, s[14:15]
	v_mov_b32_e32 v135, v133
	v_mov_b32_e32 v131, v133
	s_cmp_eq_u32 s0, 1
	s_mov_b32 s51, 0
	v_lshl_add_u64 v[8:9], s[30:31], 0, v[132:133]
	v_lshl_add_u64 v[4:5], s[30:31], 0, v[128:129]
	v_lshl_add_u64 v[2:3], s[12:13], 0, v[132:133]
	v_lshl_add_u64 v[0:1], s[12:13], 0, v[128:129]
	v_lshl_add_u64 v[6:7], s[28:29], 0, v[134:135]
	s_cselect_b64 s[12:13], -1, 0
	s_cmp_lg_u32 s0, 1
	v_lshl_add_u64 v[10:11], s[28:29], 0, v[130:131]
	s_cbranch_scc1 .LBB0_1247
	s_barrier

;     __device__ bool next(int i, pg8::Unit& u) const { const int L = i * G + c; if (L >= 1280) return false; u.pn = L >> 6; u.pm = (L & 63) + (u.pn >= 16 ? 64 : 0); return true; }
;     __host__ __device__ bool next(int i, Unit& u) const {
;         const long L = (long)i * G + c; if (L >= nwg) return false;
;         int wgid = (int)L; { const int q = nwg / NXCD, r = nwg % NXCD, xcd = wgid % NXCD, off = wgid / NXCD; wgid = (xcd < r ? xcd * (q + 1) : r * (q + 1) + (xcd - r) * q) + off; }
;         const int nig = WGM * nN, gid = wgid / nig, fm = gid * WGM, gsz = (nM - fm) < WGM ? (nM - fm) : WGM;
;         u.pm = fm + ((wgid % nig) % gsz); u.pn = (wgid % nig) / gsz; return true;
; template <class Epi> __device__ __forceinline__ void gemm8(Ctx& C, const bf16* A, const bf16* Bt, int N, int K, const Epi& E) {
;     asm volatile("" : "+s"(N), "+s"(K));
;     pg8::Gemm g{A, Bt, S, N, K}; pg8::StaticOrder so; so.init(S, N, C.nb, C.bid);
;     pg8::gemm_phase<Epi, pg8::StaticOrder, true, true>(C.lds, g, so, E, C.wave);
.LBB0_1321:
	s_movk_i32 s0, 0x800
	s_movk_i32 s4, 0x800
	s_load_dwordx2 s[6:7], s[88:89], 0xd0
	s_ashr_i32 s1, s0, 31
	s_lshr_b32 s1, s1, 24
	s_add_i32 s0, s0, s1
	s_ashr_i32 s0, s0, 8
	s_lshl_b32 s2, s0, 6
	v_readlane_b32 s1, v231, 0
	s_cmp_lt_i32 s1, s2
	s_cselect_b64 s[8:9], -1, 0
	s_cmp_ge_i32 s1, s2
	v_mbcnt_lo_u32_b32 v12, -1, 0
	v_mbcnt_hi_u32_b32 v12, -1, v12
	s_cbranch_scc1 .LBB0_1325
	s_lshl_b32 s10, s0, 2
	s_abs_i32 s11, s10
	v_cvt_f32_u32_e32 v0, s11
	v_readlane_b32 s12, v231, 0
	s_ashr_i32 s3, s12, 31
	s_lshr_b32 s3, s3, 29
	v_rcp_iflag_f32_e32 v0, v0
	s_add_i32 s3, s12, s3
	s_ashr_i32 s5, s3, 3
	s_and_b32 s3, s3, -8
	v_mul_f32_e32 v0, 0x4f7ffffe, v0
	v_cvt_u32_f32_e32 v0, v0
	s_sub_i32 s3, s12, s3
	s_lshl_b32 s1, s0, 3
	s_lshr_b32 s12, s3, 31
	s_or_b32 s1, s1, s12
	s_sub_i32 s12, 0, s11
	v_readfirstlane_b32 s13, v0
	s_mul_i32 s1, s1, s3
	s_mul_i32 s12, s12, s13
	s_add_i32 s1, s1, s5
	s_mul_hi_u32 s12, s13, s12
	s_abs_i32 s5, s1
	s_add_i32 s13, s13, s12
	s_mul_hi_u32 s12, s5, s13
	s_mul_i32 s13, s12, s11
	s_xor_b32 s3, s1, s10
	s_sub_i32 s5, s5, s13
	s_ashr_i32 s3, s3, 31
	s_add_i32 s13, s12, 1
	s_sub_i32 s14, s5, s11
	s_cmp_ge_u32 s5, s11
	s_cselect_b32 s12, s13, s12
	s_cselect_b32 s5, s14, s5
	s_add_i32 s13, s12, 1
	s_cmp_ge_u32 s5, s11
	s_cselect_b32 s5, s13, s12
	s_xor_b32 s5, s5, s3
	s_sub_i32 s3, s5, s3
	s_lshl_b32 s5, s3, 2
	s_sub_i32 s11, 64, s5
	s_min_i32 s11, s11, 4
	s_abs_i32 s12, s11
	v_cvt_f32_u32_e32 v0, s12
	s_sub_i32 s13, 0, s12
	s_mul_i32 s3, s3, s10
	s_sub_i32 s1, s1, s3
	v_rcp_iflag_f32_e32 v0, v0
	s_abs_i32 s10, s1
	s_xor_b32 s3, s1, s11
	s_ashr_i32 s3, s3, 31
	v_mul_f32_e32 v0, 0x4f7ffffe, v0
	v_cvt_u32_f32_e32 v0, v0
	s_nop 0
	v_readfirstlane_b32 s14, v0
	s_mul_i32 s13, s13, s14
	s_mul_hi_u32 s13, s14, s13
	s_add_i32 s14, s14, s13
	s_mul_hi_u32 s13, s10, s14
	s_mul_i32 s14, s13, s12
	s_sub_i32 s10, s10, s14
	s_add_i32 s14, s13, 1
	s_sub_i32 s15, s10, s12
	s_cmp_ge_u32 s10, s12
	s_cselect_b32 s13, s14, s13
	s_cselect_b32 s10, s15, s10
	s_add_i32 s14, s13, 1
	s_cmp_ge_u32 s10, s12
	s_cselect_b32 s10, s14, s13
	s_xor_b32 s10, s10, s3
	s_sub_i32 s14, s10, s3
	s_mul_i32 s3, s14, s11
	s_sub_i32 s1, s1, s3
	s_add_i32 s67, s1, s5

; __device__ __forceinline__ int lane_now() { int l; asm volatile("v_mbcnt_lo_u32_b32 %0, -1, 0\n\tv_mbcnt_hi_u32_b32 %0, -1, %0" : "=v"(l)); return l; }
; __device__ __forceinline__ void ph_norm2(Ctx& C) {
;     const int lane = lane_now(); const float* pp = (const float*)(C.ws + WS_SSQP); float* rs = (float*)(C.ws + WS_RSTD);
;     for (int row = C.gw * 64 + lane; row < S; row += C.ngw * 64) { const f32x4* p = (const f32x4*)(pp + (size_t)row * 32); float ss = 0.f;
; #pragma unroll
;         for (int q = 0; q < 8; ++q) { const f32x4 v = p[q]; ss += (v[0] + v[1]) + (v[2] + v[3]); }
;         rs[row] = 1.0f / sqrtf(ss * (1.0f / D) + 1e-6f); }
; }
.LBB0_1418:
	s_branch .LBB0_1479
	v_readlane_b32 s0, v231, 1
	v_readlane_b32 s1, v231, 2
	s_load_dwordx2 s[4:5], s[88:89], 0xd0
	s_lshl_b32 s2, s92, 6
	s_load_dword s0, s[0:1], 0xe0
	v_readlane_b32 s1, v231, 0
	s_lshl_b32 s1, s1, 9
	v_mbcnt_lo_u32_b32 v0, -1, 0
	v_mbcnt_hi_u32_b32 v0, -1, v0
	s_add_i32 s2, s2, s1
	v_add_u32_e32 v0, s2, v0
	s_movk_i32 s1, 0x4000
	v_cmp_gt_i32_e32 vcc, s1, v0
	s_and_saveexec_b64 s[6:7], vcc
	s_cbranch_execz .LBB0_1423
	s_waitcnt lgkmcnt(0)
	s_lshl_b32 s8, s0, 9
	v_ashrrev_i32_e32 v1, 31, v0
	v_mov_b64_e32 v[2:3], 0x1e600000
	s_ashr_i32 s9, s8, 31
	v_lshl_add_u64 v[2:3], v[0:1], 2, v[2:3]
	s_lshl_b64 s[10:11], s[8:9], 2
	v_lshlrev_b64 v[4:5], 7, v[0:1]
	s_lshl_b64 s[12:13], s[8:9], 7
	s_mov_b64 s[14:15], 0
	s_mov_b64 s[16:17], 0x1e400000
	s_mov_b64 s[18:19], 0x1e400040
	v_mov_b32_e32 v1, 0x358637bd
	s_mov_b32 s1, 0xf800000
	v_mov_b32_e32 v6, 0x260
	s_movk_i32 s9, 0x3fff

; __device__ __forceinline__ int lane_now() { int l; asm volatile("v_mbcnt_lo_u32_b32 %0, -1, 0\n\tv_mbcnt_hi_u32_b32 %0, -1, %0" : "=v"(l)); return l; }
; #define PH(k, ...) do { if (ka->ph_lo <= (k) && (k) < ka->ph_hi) { MKCTX(); __VA_ARGS__; if ((k) == PROBE_DUP) { GSYNC(); __VA_ARGS__; } if ((k) + 1 < ka->ph_hi) GSYNC(); } } while (0)
; __device__ __forceinline__ void ph_norm2(Ctx& C) {
;     const int lane = lane_now(); const float* pp = (const float*)(C.ws + WS_SSQP); float* rs = (float*)(C.ws + WS_RSTD);
;     for (int row = C.gw * 64 + lane; row < S; row += C.ngw * 64) { const f32x4* p = (const f32x4*)(pp + (size_t)row * 32); float ss = 0.f;
; #pragma unroll
;         for (int q = 0; q < 8; ++q) { const f32x4 v = p[q]; ss += (v[0] + v[1]) + (v[2] + v[3]); }
;         rs[row] = 1.0f / sqrtf(ss * (1.0f / D) + 1e-6f); }
; }
; template <bool COOP>
; __global__ void __launch_bounds__(NTHR, 2) mega(Args args) {
;     ...
;     PH(P_FFN1, { EpiFfn18 E{(bf16*)(C.ws + WS_HID), (const float*)(C.ws + WS_RSTD)}; gemm8(C, (const bf16*)(C.ws + WS_X2B), (const bf16*)(C.ws + WS_WGU), 2 * FF, D, E); });
.LBB0_1479:
	s_mov_b32 s101, 0
	s_load_dwordx2 s[4:5], s[88:89], 0xd0
	v_readlane_b32 s0, v231, 0
	v_mbcnt_lo_u32_b32 v0, -1, 0
	v_mbcnt_hi_u32_b32 v0, -1, v0
	s_nop 3
	s_and_b32 s1, s0, 7
	s_lshr_b32 s0, s0, 3
	s_and_b32 s0, s0, 3
	s_lshl_b32 s1, s1, 3
	s_add_i32 s0, s0, s1
	s_lshr_b32 s1, s92, 2
	s_lshl_b32 s1, s1, 2
	s_add_i32 s0, s0, s1
	s_lshl_b32 s0, s0, 8
	s_and_b32 s1, s92, 3
	s_lshl_b32 s1, s1, 6
	s_add_i32 s0, s0, s1
	v_add_u32_e32 v0, s0, v0
	v_lshlrev_b32_e32 v2, 7, v0
	v_mov_b32_e32 v3, 0
	s_waitcnt lgkmcnt(0)
	v_lshl_add_u64 v[2:3], s[4:5], 0, v[2:3]
	s_mov_b64 s[6:7], 0x1e400000
	v_lshl_add_u64 v[2:3], v[2:3], 0, s[6:7]
	global_load_dwordx4 v[4:7], v[2:3], off
	global_load_dwordx4 v[8:11], v[2:3], off offset:16
	global_load_dwordx4 v[12:15], v[2:3], off offset:32
	global_load_dwordx4 v[16:19], v[2:3], off offset:48
	global_load_dwordx4 v[20:23], v[2:3], off offset:64
	global_load_dwordx4 v[24:27], v[2:3], off offset:80
	global_load_dwordx4 v[28:31], v[2:3], off offset:96
	global_load_dwordx4 v[32:35], v[2:3], off offset:112
	v_mov_b32_e32 v36, 0
	s_waitcnt vmcnt(7)
	v_add_f32_e32 v37, v4, v5
	v_add_f32_e32 v38, v6, v7
	v_add_f32_e32 v37, v37, v38
	v_add_f32_e32 v36, v36, v37
	s_waitcnt vmcnt(6)
	v_add_f32_e32 v37, v8, v9
	v_add_f32_e32 v38, v10, v11
	v_add_f32_e32 v37, v37, v38
	v_add_f32_e32 v36, v36, v37
	s_waitcnt vmcnt(5)
	v_add_f32_e32 v37, v12, v13
	v_add_f32_e32 v38, v14, v15
	v_add_f32_e32 v37, v37, v38
	v_add_f32_e32 v36, v36, v37
	s_waitcnt vmcnt(4)
	v_add_f32_e32 v37, v16, v17
	v_add_f32_e32 v38, v18, v19
	v_add_f32_e32 v37, v37, v38
	v_add_f32_e32 v36, v36, v37
	s_waitcnt vmcnt(3)
	v_add_f32_e32 v37, v20, v21
	v_add_f32_e32 v38, v22, v23
	v_add_f32_e32 v37, v37, v38
	v_add_f32_e32 v36, v36, v37
	s_waitcnt vmcnt(2)
	v_add_f32_e32 v37, v24, v25
	v_add_f32_e32 v38, v26, v27
	v_add_f32_e32 v37, v37, v38
	v_add_f32_e32 v36, v36, v37
	s_waitcnt vmcnt(1)
	v_add_f32_e32 v37, v28, v29
	v_add_f32_e32 v38, v30, v31
	v_add_f32_e32 v37, v37, v38
	v_add_f32_e32 v36, v36, v37
	s_waitcnt vmcnt(0)
	v_add_f32_e32 v37, v32, v33
	v_add_f32_e32 v38, v34, v35
	v_add_f32_e32 v37, v37, v38
	v_add_f32_e32 v36, v36, v37
	v_mov_b32_e32 v37, 0x358637bd
	v_fmamk_f32 v36, v36, 0x3a000000, v37
	v_rsq_f32_e32 v36, v36
	v_lshlrev_b32_e32 v38, 2, v0
	v_mov_b32_e32 v39, 0
	v_lshl_add_u64 v[38:39], s[4:5], 0, v[38:39]
	s_mov_b64 s[6:7], 0x1e600000
	v_lshl_add_u64 v[38:39], v[38:39], 0, s[6:7]
	global_store_dword v[38:39], v36, off
	s_waitcnt vmcnt(0)
	s_barrier
	v_readlane_b32 s0, v231, 1
	v_readlane_b32 s1, v231, 2
	s_load_dword s48, s[0:1], 0xe0
	s_movk_i32 s0, 0x2c00
	s_movk_i32 s4, 0x800
	s_load_dwordx2 s[10:11], s[88:89], 0xd0
	s_ashr_i32 s1, s0, 31
	s_lshr_b32 s1, s1, 24
	s_add_i32 s0, s0, s1
	s_ashr_i32 s1, s0, 8
	s_lshl_b32 s2, s1, 6
	v_readlane_b32 s0, v231, 0
	s_cmp_ge_i32 s0, s2
	v_mbcnt_lo_u32_b32 v12, -1, 0
	v_mbcnt_hi_u32_b32 v12, -1, v12
	s_cbranch_scc1 .LBB0_1502
; __device__ __forceinline__ int lane_now() { int l; asm volatile("v_mbcnt_lo_u32_b32 %0, -1, 0\n\tv_mbcnt_hi_u32_b32 %0, -1, %0" : "=v"(l)); return l; }
; #define PG8_STAGE(bufoff, gbase, voff) do { _Pragma("unroll") for (int _i = 0; _i < 2; ++_i) \
;         __builtin_amdgcn_global_load_lds((const unsigned*)((const char*)(gbase) + (voff)[_i]), (PG8_LAS unsigned*)(lds + (bufoff) + ldsw + _i * 8192), 16, 0, 0); } while (0)
; template <class Epi, class Sched, bool ALIGN_EPI = false, bool SP2 = false>
; __device__ __forceinline__ void gemm_phase(PG8_LAS unsigned char* lds, const Gemm g, const Sched& S, const Epi& E, const int wid) {
;     const int lane = lane_now(), tid = wid * 64 + lane, wr = wid >> 2, wc = wid & 3, fr = lane & 15, fq = lane >> 4;
;     const int K = g.K, nt = K / BK;
;     unsigned voffA[2], voffB[2];
; #pragma unroll
;     for (int i = 0; i < 2; ++i) { int R, C; stage_rc(tid * 16 + i * 8192, R, C); const int Rb = Epi::PERM ? ((R & ~31) + perm32(R & 31)) : R;
;         voffA[i] = (unsigned)(R * K + C) * 2u; voffB[i] = (unsigned)(Rb * K + C) * 2u; }
;     const size_t kstep = (size_t)(BK * 2);
;     const size_t hstep = (size_t)HALF * K * 2;
;     const size_t tstep = 2 * hstep;
;     const unsigned ldsw = (unsigned)wid * 1024u;
;     const int aoff = lds_byte(wr * 64 + fr, fq * 8), boff = lds_byte(wc * 32 + fr, fq * 8);
;     ...
;     Unit cur, nxt; int ui = 0;
;     if (!S.next(0, cur)) return;
;     f32x4 acc[2][2][4][2];
; #pragma unroll
;     for (int a = 0; a < 2; ++a)
; #pragma unroll
;         for (int b = 0; b < 2; ++b)
; #pragma unroll
;             for (int m = 0; m < 4; ++m)
; #pragma unroll
;                 for (int n = 0; n < 2; ++n) acc[a][b][m][n] = (f32x4){0.f, 0.f, 0.f, 0.f};
;     bf16x8 At[4][2], B0[2][2], B1[2][2];
;     const char* cA = (const char*)g.A + (size_t)cur.pm * tstep; const char* cB = (const char*)g.Bt + (size_t)cur.pn * tstep;
;     S.a_ready(cur);
;     if constexpr (SP2) {
;         PG8_STAGE(PG8_SB(0, 0), cB, voffB); PG8_STAGE(PG8_SB(0, 1), cB + hstep, voffB); PG8_STAGE(PG8_SA(0, 0), cA, voffA); PG8_STAGE(PG8_SA(0, 1), cA + hstep, voffA);
;         if (wr == 1) PG8_BAR;
;         PG8_WAIT_V(2); PG8_BAR;
;         PG8_STAGE(PG8_SB(1, 0), cB + kstep, voffB); PG8_STAGE(PG8_SA(1, 0), cA + kstep, voffA); PG8_STAGE(PG8_SB(1, 1), cB + hstep + kstep, voffB);
;         PG8_WAIT_V(6); PG8_BAR;
	s_waitcnt lgkmcnt(0)
	s_add_u32 s30, s10, 0x1a400000
	s_addc_u32 s31, s11, 0
	s_add_u32 s34, s10, 0xe200000
	s_addc_u32 s35, s11, 0
	s_lshl_b32 s36, s92, 10
	v_lshl_add_u32 v0, v12, 4, s36
	v_add_u32_e32 v1, 0x2000, v0
	v_ashrrev_i32_e32 v2, 31, v1
	v_lshrrev_b32_e32 v2, 22, v2
	v_add_u32_e32 v2, v1, v2
	v_ashrrev_i32_e32 v2, 10, v2
	v_mul_i32_i24_e32 v3, 0x400, v2
	v_sub_u32_e32 v1, v1, v3
	v_lshrrev_b32_e32 v3, 4, v1
	v_bitop3_b32 v1, v3, v1, 32 bitop3:0x6c
	v_ashrrev_i32_e32 v3, 31, v1
	v_lshrrev_b32_e32 v3, 26, v3
	v_add_u32_e32 v3, v1, v3
	v_lshlrev_b32_e32 v5, 3, v2
	v_lshlrev_b32_e32 v2, 5, v2
	v_and_b32_e32 v13, 32, v2
	v_and_b32_e32 v2, 0xffc0, v3
	v_sub_u32_e32 v1, v1, v2
	v_ashrrev_i32_e32 v4, 6, v3
	v_and_b32_e32 v5, -16, v5
	v_lshrrev_b16_e32 v2, 7, v1
	v_add_u32_e32 v5, v4, v5
	v_and_b32_e32 v2, 1, v2
	v_and_b32_e32 v4, 3, v4
	s_mov_b32 s3, 0x7fffffe0
	v_lshrrev_b32_e32 v6, 2, v5
	v_lshlrev_b32_e32 v7, 1, v5
	v_add_u16_e32 v1, v1, v2
	v_mov_b32_e32 v2, 1
	v_and_or_b32 v4, v5, s3, v4
	v_and_b32_e32 v6, 4, v6
	v_and_b32_e32 v7, 24, v7
	v_ashrrev_i16_sdwa v1, v2, sext(v1) dst_sel:DWORD dst_unused:UNUSED_PAD src0_sel:DWORD src1_sel:BYTE_0
	v_or3_b32 v4, v4, v6, v7
	v_bfe_i32 v14, v1, 0, 16
	v_mul_lo_u32 v4, v4, s4
	v_add_u32_e32 v1, v13, v14
	v_mul_lo_u32 v15, v5, s4
	s_waitcnt vmcnt(0)
	v_add_lshl_u32 v128, v4, v1, 1
	v_add_lshl_u32 v130, v1, v15, 1
	v_ashrrev_i32_e32 v1, 31, v0
	v_lshrrev_b32_e32 v1, 22, v1
	v_add_u32_e32 v1, v0, v1
	v_ashrrev_i32_e32 v1, 10, v1
	v_mul_i32_i24_e32 v3, 0x400, v1
	v_sub_u32_e32 v0, v0, v3
	v_lshrrev_b32_e32 v3, 4, v0
	v_bitop3_b32 v0, v3, v0, 32 bitop3:0x6c
	v_ashrrev_i32_e32 v3, 31, v0
	v_lshrrev_b32_e32 v3, 26, v3
	v_add_u32_e32 v3, v0, v3
	v_lshlrev_b32_e32 v5, 3, v1
	v_ashrrev_i32_e32 v4, 6, v3
	v_and_b32_e32 v5, -16, v5
	v_readlane_b32 s7, v231, 0
	v_add_u32_e32 v5, v4, v5
	v_and_b32_e32 v4, 3, v4
	s_ashr_i32 s38, s7, 31
	v_and_or_b32 v4, v5, s3, v4
	s_lshr_b32 s3, s38, 29
	s_add_i32 s3, s7, s3
	s_ashr_i32 s5, s4, 31
	s_lshl_b32 s37, s1, 3
	s_ashr_i32 s6, s3, 3
	s_and_b32 s3, s3, -8
	s_ashr_i32 s0, s92, 2
	s_lshl_b64 s[12:13], s[4:5], 8
	s_lshl_b64 s[14:15], s[4:5], 9
	s_sub_i32 s3, s7, s3
	s_or_b32 s39, s37, 1
	s_cmp_lt_i32 s3, 0
	v_lshlrev_b32_e32 v1, 5, v1
	s_cselect_b32 s7, s39, s37
	s_lshl_b32 s40, s1, 2
	v_and_b32_e32 v16, 32, v1
	v_and_b32_e32 v1, 0xc0, v3
	s_abs_i32 s41, s40
	v_sub_u32_e32 v0, v0, v1
	v_cvt_f32_u32_e32 v1, s41
	s_mul_i32 s3, s7, s3
	s_sub_i32 s7, 0, s41
	s_add_i32 s3, s3, s6
	v_rcp_iflag_f32_e32 v1, v1
	s_ashr_i32 s6, s3, 31
	s_bfe_i32 s42, s1, 0x1001d
	s_xor_b32 s1, s6, s42
	v_mul_f32_e32 v1, 0x4f7ffffe, v1
	v_cvt_u32_f32_e32 v1, v1
	s_abs_i32 s6, s3
	v_lshrrev_b32_e32 v6, 2, v5
	v_lshlrev_b32_e32 v7, 1, v5
	v_readfirstlane_b32 s43, v1
	s_mul_i32 s7, s7, s43
	s_mul_hi_u32 s7, s43, s7
	s_add_i32 s43, s43, s7
	s_mul_hi_u32 s7, s6, s43
	s_mul_i32 s8, s7, s41
	s_sub_i32 s6, s6, s8
	s_add_i32 s8, s7, 1
	s_sub_i32 s9, s6, s41
	s_cmp_ge_u32 s6, s41
	s_cselect_b32 s7, s8, s7
	s_cselect_b32 s6, s9, s6
	s_add_i32 s8, s7, 1
	s_cmp_ge_u32 s6, s41
	s_cselect_b32 s6, s8, s7
	s_xor_b32 s6, s6, s1
	s_sub_i32 s1, s6, s1
	s_lshl_b32 s6, s1, 2
	s_sub_i32 s7, 64, s6
	s_min_i32 s7, s7, 4
	s_abs_i32 s8, s7
	v_cvt_f32_u32_e32 v1, s8
	v_and_b32_e32 v6, 4, v6
	v_and_b32_e32 v7, 24, v7
	v_ashrrev_i16_sdwa v0, v2, sext(v0) dst_sel:DWORD dst_unused:UNUSED_PAD src0_sel:DWORD src1_sel:BYTE_0
	v_or3_b32 v4, v4, v6, v7
	v_bfe_i32 v17, v0, 0, 16
	v_mul_lo_u32 v4, v4, s4
	v_add_u32_e32 v0, v16, v17
	v_mul_lo_u32 v18, v5, s4
	v_add_lshl_u32 v132, v4, v0, 1
	v_add_lshl_u32 v134, v0, v18, 1
	v_rcp_iflag_f32_e32 v0, v1
	s_sub_i32 s16, 0, s8
	s_mul_i32 s1, s1, s40
	s_sub_i32 s1, s3, s1
	v_mul_f32_e32 v0, 0x4f7ffffe, v0
	v_cvt_u32_f32_e32 v0, v0
	s_abs_i32 s9, s1
	s_xor_b32 s3, s1, s7
	s_ashr_i32 s3, s3, 31
	v_readfirstlane_b32 s17, v0
	s_mul_i32 s16, s16, s17
	s_mul_hi_u32 s16, s17, s16
	s_add_i32 s17, s17, s16
	s_mul_hi_u32 s16, s9, s17
	s_mul_i32 s17, s16, s8
	s_sub_i32 s9, s9, s17
	s_add_i32 s17, s16, 1
	s_sub_i32 s18, s9, s8
	s_cmp_ge_u32 s9, s8
	s_cselect_b32 s16, s17, s16
	s_cselect_b32 s9, s18, s9
	s_add_i32 s17, s16, 1
	s_cmp_ge_u32 s9, s8
	s_cselect_b32 s8, s17, s16
	s_xor_b32 s8, s8, s3
	s_sub_i32 s62, s8, s3
	s_mul_i32 s3, s62, s7
	s_sub_i32 s1, s1, s3
	s_add_i32 s63, s1, s6
	s_lshr_b64 s[6:7], s[4:5], 23
	s_ashr_i32 s1, s63, 31
	s_ashr_i32 s7, s62, 31
	s_mul_i32 s1, s14, s1
	s_mul_hi_u32 s3, s14, s63
	s_mul_i32 s7, s14, s7
	s_mul_hi_u32 s8, s14, s62
	s_add_i32 s1, s3, s1
	s_mul_i32 s3, s6, s63
	s_add_i32 s7, s8, s7
	s_mul_i32 s6, s6, s62
	s_add_i32 s1, s1, s3
	s_add_i32 s7, s7, s6
	s_mul_i32 s6, s14, s62
	s_add_u32 s6, s34, s6
	s_addc_u32 s7, s35, s7
	s_add_i32 s44, s36, 0
	s_add_i32 m0, s44, 0x10000
	s_mul_i32 s3, s14, s63
	global_load_lds_dwordx4 v132, s[6:7]
	s_add_i32 m0, s44, 0x12000
	s_add_u32 s16, s6, s12
	global_load_lds_dwordx4 v128, s[6:7]
	s_addc_u32 s17, s7, s13
	s_add_i32 m0, s44, 0x14000
	v_mov_b32_e32 v133, 0
	global_load_lds_dwordx4 v132, s[16:17]
	s_add_i32 m0, s44, 0x16000
	s_add_u32 s8, s30, s3
	s_addc_u32 s9, s31, s1
	s_add_i32 s45, s44, 0x2000
	global_load_lds_dwordx4 v128, s[16:17]
	s_mov_b32 m0, s44
	s_add_u32 s18, s8, s12
	global_load_lds_dwordx4 v134, s[8:9]
	s_mov_b32 m0, s45
	s_addc_u32 s19, s9, s13
	s_add_i32 s46, s44, 0x4000
	global_load_lds_dwordx4 v130, s[8:9]
	s_mov_b32 m0, s46
	s_add_i32 s47, s44, 0x6000
	global_load_lds_dwordx4 v134, s[18:19]
	s_mov_b32 m0, s47
	v_mov_b32_e32 v129, v133
	global_load_lds_dwordx4 v130, s[18:19]
	v_mov_b32_e32 v135, v133
	v_mov_b32_e32 v131, v133
	s_cmp_eq_u32 s0, 1
	s_mov_b32 s49, 0
	v_lshl_add_u64 v[8:9], s[6:7], 0, v[132:133]
	v_lshl_add_u64 v[4:5], s[6:7], 0, v[128:129]
	v_lshl_add_u64 v[2:3], s[16:17], 0, v[132:133]
	v_lshl_add_u64 v[0:1], s[16:17], 0, v[128:129]
	v_lshl_add_u64 v[6:7], s[8:9], 0, v[134:135]
	s_cselect_b64 s[16:17], -1, 0
	s_cmp_lg_u32 s0, 1
	v_lshl_add_u64 v[10:11], s[8:9], 0, v[130:131]
	s_cbranch_scc1 .LBB0_1484
	s_barrier

; __device__ __forceinline__ int lane_now() { int l; asm volatile("v_mbcnt_lo_u32_b32 %0, -1, 0\n\tv_mbcnt_hi_u32_b32 %0, -1, %0" : "=v"(l)); return l; }
; #define PG8_BAR __builtin_amdgcn_s_barrier()
; template <class Epi, class Sched, bool ALIGN_EPI = false, bool SP2 = false>
; __device__ __forceinline__ void gemm_phase(PG8_LAS unsigned char* lds, const Gemm g, const Sched& S, const Epi& E, const int wid) {
;     const int lane = lane_now(), tid = wid * 64 + lane, wr = wid >> 2, wc = wid & 3, fr = lane & 15, fq = lane >> 4;
;     const int K = g.K, nt = K / BK;
;     unsigned voffA[2], voffB[2];
; #pragma unroll
;     for (int i = 0; i < 2; ++i) { int R, C; stage_rc(tid * 16 + i * 8192, R, C); const int Rb = Epi::PERM ? ((R & ~31) + perm32(R & 31)) : R;
;         voffA[i] = (unsigned)(R * K + C) * 2u; voffB[i] = (unsigned)(Rb * K + C) * 2u; }
;     const size_t kstep = (size_t)(BK * 2);
;     const size_t hstep = (size_t)HALF * K * 2;
;     const size_t tstep = 2 * hstep;
;     const unsigned ldsw = (unsigned)wid * 1024u;
;     const int aoff = lds_byte(wr * 64 + fr, fq * 8), boff = lds_byte(wc * 32 + fr, fq * 8);
;     ...
;     Unit cur, nxt; int ui = 0;
;     if (!S.next(0, cur)) return;
;     f32x4 acc[2][2][4][2];
; #pragma unroll
;     for (int a = 0; a < 2; ++a)
; #pragma unroll
;         for (int b = 0; b < 2; ++b)
; #pragma unroll
;             for (int m = 0; m < 4; ++m)
; #pragma unroll
;                 for (int n = 0; n < 2; ++n) acc[a][b][m][n] = (f32x4){0.f, 0.f, 0.f, 0.f};
;     bf16x8 At[4][2], B0[2][2], B1[2][2];
;     const char* cA = (const char*)g.A + (size_t)cur.pm * tstep; const char* cB = (const char*)g.Bt + (size_t)cur.pn * tstep;
;     S.a_ready(cur);
;     if constexpr (SP2) {
;         PG8_STAGE(PG8_SB(0, 0), cB, voffB); PG8_STAGE(PG8_SB(0, 1), cB + hstep, voffB); PG8_STAGE(PG8_SA(0, 0), cA, voffA); PG8_STAGE(PG8_SA(0, 1), cA + hstep, voffA);
;         if (wr == 1) PG8_BAR;
;         PG8_WAIT_V(2); PG8_BAR;
;         PG8_STAGE(PG8_SB(1, 0), cB + kstep, voffB); PG8_STAGE(PG8_SA(1, 0), cA + kstep, voffA); PG8_STAGE(PG8_SB(1, 1), cB + hstep + kstep, voffB);
;         PG8_WAIT_V(6); PG8_BAR;
; template <bool COOP>
; __global__ void __launch_bounds__(NTHR, 2) mega(Args args) {
;     ...
;     PH(P_FFN2, { EpiResB8 E{(const bf16*)(C.ws + WS_X2B), C.out}; gemm8(C, (const bf16*)(C.ws + WS_HID), (const bf16*)(C.ws + WS_WD), D, FF, E); });
.LBB0_1558:
	v_readlane_b32 s0, v231, 1
	v_readlane_b32 s1, v231, 2
	s_load_dword s46, s[0:1], 0xe0
	s_movk_i32 s0, 0x800
	s_movk_i32 s2, 0x1600
	s_load_dwordx4 s[4:7], s[88:89], 0xc8
	s_ashr_i32 s1, s0, 31
	s_lshr_b32 s1, s1, 24
	s_add_i32 s0, s0, s1
	s_ashr_i32 s12, s0, 8
	s_lshl_b32 s0, s12, 6
	v_readlane_b32 s16, v231, 0
	s_cmp_ge_i32 s16, s0
	v_mbcnt_lo_u32_b32 v12, -1, 0
	v_mbcnt_hi_u32_b32 v12, -1, v12
	s_cbranch_scc1 .LBB0_1581
	s_waitcnt lgkmcnt(0)
	s_add_u32 s44, s6, 0x10e00000
	s_addc_u32 s45, s7, 0
	s_lshl_b32 s47, s92, 10
	v_lshl_add_u32 v2, v12, 4, s47
	v_add_u32_e32 v0, 0x2000, v2
	v_ashrrev_i32_e32 v1, 31, v0
	v_lshrrev_b32_e32 v1, 22, v1
	v_add_u32_e32 v1, v0, v1
	v_ashrrev_i32_e32 v1, 10, v1
	v_mul_i32_i24_e32 v3, 0x400, v1
	v_sub_u32_e32 v0, v0, v3
	v_lshrrev_b32_e32 v3, 4, v0
	v_bitop3_b32 v3, v3, v0, 32 bitop3:0x6c
	v_ashrrev_i32_e32 v0, 31, v3
	v_lshrrev_b32_e32 v0, 26, v0
	v_add_u32_e32 v4, v3, v0
	v_lshlrev_b32_e32 v5, 3, v1
	v_ashrrev_i32_e32 v0, 6, v4
	v_and_b32_e32 v5, 0x7ffffff0, v5
	v_add_u32_e32 v5, v0, v5
	v_lshlrev_b32_e32 v0, 5, v1
	v_and_b32_e32 v0, 32, v0
	v_mad_u64_u32 v[0:1], s[14:15], v5, s2, v[0:1]
	v_and_b32_e32 v1, 0xffc0, v4
	v_sub_u32_e32 v1, v3, v1
	v_lshrrev_b16_e32 v3, 7, v1
	v_and_b32_e32 v3, 1, v3
	v_add_u16_e32 v1, v1, v3
	v_mov_b32_e32 v3, 1
	v_ashrrev_i16_sdwa v1, v3, sext(v1) dst_sel:DWORD dst_unused:UNUSED_PAD src0_sel:DWORD src1_sel:BYTE_0
	v_bfe_i32 v1, v1, 0, 16
	s_waitcnt vmcnt(0)
	v_add_lshl_u32 v128, v0, v1, 1
	v_ashrrev_i32_e32 v0, 31, v2
	v_lshrrev_b32_e32 v0, 22, v0
	v_add_u32_e32 v0, v2, v0
	v_ashrrev_i32_e32 v0, 10, v0
	v_mul_i32_i24_e32 v1, 0x400, v0
	v_sub_u32_e32 v1, v2, v1
	v_lshrrev_b32_e32 v2, 4, v1
	v_bitop3_b32 v2, v2, v1, 32 bitop3:0x6c
	v_ashrrev_i32_e32 v1, 31, v2
	v_lshrrev_b32_e32 v1, 26, v1
	v_add_u32_e32 v4, v2, v1
	v_lshlrev_b32_e32 v5, 3, v0
	v_ashrrev_i32_e32 v1, 6, v4
	v_and_b32_e32 v5, 0x7ffffff0, v5
	v_lshlrev_b32_e32 v0, 5, v0
	s_ashr_i32 s49, s16, 31
	v_add_u32_e32 v1, v1, v5
	v_and_b32_e32 v0, 32, v0
	s_lshr_b32 s13, s49, 29
	v_mad_u64_u32 v[0:1], s[14:15], v1, s2, v[0:1]
	s_add_i32 s13, s16, s13
	s_ashr_i32 s3, s2, 31
	s_lshl_b32 s48, s12, 3
	s_ashr_i32 s14, s13, 3
	s_and_b32 s13, s13, -8
	s_ashr_i32 s1, s92, 2
	s_lshl_b64 s[8:9], s[2:3], 8
	s_lshl_b64 s[10:11], s[2:3], 9
	s_sub_i32 s13, s16, s13
	s_or_b32 s50, s48, 1
	s_cmp_lt_i32 s13, 0
	s_cselect_b32 s15, s50, s48
	s_lshl_b32 s51, s12, 2
	s_abs_i32 s52, s51
	v_cvt_f32_u32_e32 v1, s52
	s_mul_i32 s13, s15, s13
	s_sub_i32 s15, 0, s52
	s_add_i32 s13, s13, s14
	v_rcp_iflag_f32_e32 v1, v1
	s_ashr_i32 s14, s13, 31
	s_bfe_i32 s53, s12, 0x1001d
	s_xor_b32 s12, s14, s53
	v_mul_f32_e32 v1, 0x4f7ffffe, v1
	v_cvt_u32_f32_e32 v1, v1
	s_abs_i32 s14, s13
	v_and_b32_e32 v4, 0xc0, v4
	v_sub_u32_e32 v2, v2, v4
	v_readfirstlane_b32 s54, v1
	s_mul_i32 s15, s15, s54
	s_mul_hi_u32 s15, s54, s15
	s_add_i32 s54, s54, s15
	s_mul_hi_u32 s15, s14, s54
	s_mul_i32 s16, s15, s52
	s_sub_i32 s14, s14, s16
	s_add_i32 s16, s15, 1
	s_sub_i32 s17, s14, s52
	s_cmp_ge_u32 s14, s52
	s_cselect_b32 s15, s16, s15
	s_cselect_b32 s14, s17, s14
	s_add_i32 s16, s15, 1
	s_cmp_ge_u32 s14, s52
	s_cselect_b32 s14, s16, s15
	s_xor_b32 s14, s14, s12
	s_sub_i32 s12, s14, s12
	s_lshl_b32 s14, s12, 2
	s_sub_i32 s15, 64, s14
	s_min_i32 s15, s15, 4
	s_abs_i32 s16, s15
	v_cvt_f32_u32_e32 v1, s16
	v_ashrrev_i16_sdwa v2, v3, sext(v2) dst_sel:DWORD dst_unused:UNUSED_PAD src0_sel:DWORD src1_sel:BYTE_0
	v_bfe_i32 v2, v2, 0, 16
	v_add_lshl_u32 v130, v0, v2, 1
	v_rcp_iflag_f32_e32 v0, v1
	s_sub_i32 s18, 0, s16
	s_mul_i32 s12, s12, s51
	s_sub_i32 s12, s13, s12
	v_mul_f32_e32 v0, 0x4f7ffffe, v0
	v_cvt_u32_f32_e32 v0, v0
	s_abs_i32 s17, s12
	s_xor_b32 s13, s12, s15
	s_ashr_i32 s13, s13, 31
	v_readfirstlane_b32 s19, v0
	s_mul_i32 s18, s18, s19
	s_mul_hi_u32 s18, s19, s18
	s_add_i32 s19, s19, s18
	s_mul_hi_u32 s18, s17, s19
	s_mul_i32 s19, s18, s16
	s_sub_i32 s17, s17, s19
	s_add_i32 s19, s18, 1
	s_sub_i32 s20, s17, s16
	s_cmp_ge_u32 s17, s16
	s_cselect_b32 s18, s19, s18
	s_cselect_b32 s17, s20, s17
	s_add_i32 s19, s18, 1
	s_cmp_ge_u32 s17, s16
	s_cselect_b32 s16, s19, s18
	s_xor_b32 s16, s16, s13
	s_sub_i32 s71, s16, s13
	s_mul_i32 s13, s71, s15
	s_sub_i32 s12, s12, s13
	s_add_i32 s72, s12, s14
	s_ashr_i32 s12, s72, 31
	s_mul_i32 s12, s10, s12
	s_mul_hi_u32 s13, s10, s72
	s_add_i32 s14, s13, s12
	s_lshr_b64 s[12:13], s[2:3], 23
	s_mul_i32 s13, s12, s72
	s_add_i32 s14, s14, s13
	s_ashr_i32 s13, s71, 31
	s_mul_i32 s13, s10, s13
	s_mul_hi_u32 s16, s10, s71
	s_add_i32 s13, s16, s13
	s_mul_i32 s12, s12, s71
	s_add_i32 s13, s13, s12
	s_mul_i32 s12, s10, s71
	s_add_u32 s42, s44, s12
	s_addc_u32 s43, s45, s13
	s_add_i32 s55, s47, 0
	s_add_i32 m0, s55, 0x10000
	s_mul_i32 s15, s10, s72
	global_load_lds_dwordx4 v130, s[42:43]
	s_add_i32 m0, s55, 0x12000
	s_add_u32 s12, s42, s8
	global_load_lds_dwordx4 v128, s[42:43]
	s_addc_u32 s13, s43, s9
	s_add_i32 m0, s55, 0x14000
	v_mov_b32_e32 v131, 0
	global_load_lds_dwordx4 v130, s[12:13]
	s_add_i32 m0, s55, 0x16000
	s_add_u32 s40, s6, s15
	s_addc_u32 s41, s7, s14
	s_add_i32 s56, s55, 0x2000
	global_load_lds_dwordx4 v128, s[12:13]
	s_mov_b32 m0, s55
	s_add_u32 s14, s40, s8
	global_load_lds_dwordx4 v130, s[40:41]
	s_mov_b32 m0, s56
	s_addc_u32 s15, s41, s9
	s_add_i32 s57, s55, 0x4000
	global_load_lds_dwordx4 v128, s[40:41]
	s_mov_b32 m0, s57
	s_add_i32 s58, s55, 0x6000
	global_load_lds_dwordx4 v130, s[14:15]
	s_mov_b32 m0, s58
	v_mov_b32_e32 v129, v131
	global_load_lds_dwordx4 v128, s[14:15]
	s_cmp_eq_u32 s1, 1
	s_mov_b32 s59, 0
	v_lshl_add_u64 v[10:11], s[42:43], 0, v[130:131]
	v_lshl_add_u64 v[8:9], s[42:43], 0, v[128:129]
	v_lshl_add_u64 v[2:3], s[12:13], 0, v[130:131]
	v_lshl_add_u64 v[0:1], s[12:13], 0, v[128:129]
	v_lshl_add_u64 v[4:5], s[40:41], 0, v[130:131]
	s_cselect_b64 s[12:13], -1, 0
	s_cmp_lg_u32 s1, 1
	v_lshl_add_u64 v[6:7], s[40:41], 0, v[128:129]
	s_cbranch_scc1 .LBB0_1563
	s_barrier

.LBB0_1581:
	s_branch .LBB0_1637
	s_getreg_b32 s4, hwreg(HW_REG_XCC_ID, 0, 4)
	s_cmp_lg_u32 s92, 0
	s_mov_b64 s[2:3], 0
	s_cbranch_scc1 .LBB0_1584
	v_mbcnt_lo_u32_b32 v0, -1, 0
	v_mbcnt_hi_u32_b32 v0, -1, v0
	s_nop 0
	v_cmp_eq_u32_e32 vcc, 0, v0
	s_and_b64 s[2:3], vcc, exec
